# K-loops: staged lgkmcnt waits before the first MFMA that needs each fragment, re-tested under the static-priority regime
# baseline (speedup 1.0000x reference)
.Lkprio_5:
.LBB0_57:
	s_add_u32 s22, s0, 0xfffc0080
	s_addc_u32 s23, s1, -1
	s_add_i32 s65, 0, 0x10000
	v_add_u32_e32 v142, s65, v178
	ds_read_b128 v[130:133], v142
	ds_read_b128 v[134:137], v142 offset:1024
	ds_read_b128 v[138:141], v142 offset:2048
	ds_read_b128 v[142:145], v142 offset:3072
	s_cmp_eq_u32 s64, 12
	s_cselect_b32 s49, s37, s23
	s_cselect_b32 s48, s60, s22
	s_cselect_b32 s23, s35, s63
	s_cselect_b32 s22, s61, s62
	v_lshl_add_u64 v[186:187], s[0:1], 0, v[168:169]
	s_add_i32 m0, s47, 0xc000
	ds_read_b128 v[172:175], v180
	ds_read_b128 v[182:185], v180 offset:1024
	ds_read_b128 v[206:209], v180 offset:2048
	ds_read_b128 v[210:213], v180 offset:3072
	ds_read_b128 v[214:217], v180 offset:4096
	ds_read_b128 v[218:221], v180 offset:5120
	ds_read_b128 v[222:225], v180 offset:6144
	ds_read_b128 v[226:229], v180 offset:7168
	global_load_lds_dwordx4 v[186:187], off
	s_add_i32 m0, s47, 0xe000
	v_lshl_add_u64 v[186:187], s[0:1], 0, v[170:171]
	global_load_lds_dwordx4 v[186:187], off
	s_waitcnt lgkmcnt(8)
	s_barrier
	s_waitcnt lgkmcnt(7)
	v_mfma_f32_16x16x32_bf16 v[126:129], v[130:133], v[172:175], v[126:129]
	v_mfma_f32_16x16x32_bf16 v[122:125], v[138:141], v[172:175], v[122:125]
	s_waitcnt lgkmcnt(5)
	v_mfma_f32_16x16x32_bf16 v[114:117], v[130:133], v[206:209], v[114:117]
	v_mfma_f32_16x16x32_bf16 v[106:109], v[138:141], v[206:209], v[106:109]
	s_waitcnt lgkmcnt(3)
	v_mfma_f32_16x16x32_bf16 v[98:101], v[130:133], v[214:217], v[98:101]
	v_mfma_f32_16x16x32_bf16 v[90:93], v[138:141], v[214:217], v[90:93]
	s_waitcnt lgkmcnt(1)
	v_mfma_f32_16x16x32_bf16 v[82:85], v[130:133], v[222:225], v[82:85]
	v_mfma_f32_16x16x32_bf16 v[74:77], v[138:141], v[222:225], v[74:77]
	v_mfma_f32_16x16x32_bf16 v[126:129], v[134:137], v[182:185], v[126:129]
	v_mfma_f32_16x16x32_bf16 v[122:125], v[142:145], v[182:185], v[122:125]
	v_mfma_f32_16x16x32_bf16 v[114:117], v[134:137], v[210:213], v[114:117]
	v_mfma_f32_16x16x32_bf16 v[106:109], v[142:145], v[210:213], v[106:109]
	v_mfma_f32_16x16x32_bf16 v[98:101], v[134:137], v[218:221], v[98:101]
	v_mfma_f32_16x16x32_bf16 v[90:93], v[142:145], v[218:221], v[90:93]
	s_waitcnt lgkmcnt(0)
	v_mfma_f32_16x16x32_bf16 v[82:85], v[134:137], v[226:229], v[82:85]
	v_mfma_f32_16x16x32_bf16 v[74:77], v[142:145], v[226:229], v[74:77]
	s_barrier
	s_add_i32 s68, 0, 0x14000
	s_add_i32 s65, s65, s27
	v_add_u32_e32 v181, s68, v178
	v_lshl_add_u64 v[186:187], s[22:23], 0, v[0:1]
	s_mov_b32 m0, s65
	ds_read_b128 v[230:233], v181
	ds_read_b128 v[234:237], v181 offset:1024
	ds_read_b128 v[238:241], v181 offset:2048
	ds_read_b128 v[242:245], v181 offset:3072
	global_load_lds_dwordx4 v[186:187], off
	s_add_i32 m0, s65, 0x2000
	v_lshl_add_u64 v[246:247], s[22:23], 0, v[166:167]
	global_load_lds_dwordx4 v[246:247], off
	s_barrier
	s_waitcnt lgkmcnt(3)
	v_mfma_f32_16x16x32_bf16 v[118:121], v[230:233], v[172:175], v[118:121]
	s_waitcnt lgkmcnt(1)
	v_mfma_f32_16x16x32_bf16 v[110:113], v[238:241], v[172:175], v[110:113]
	v_mfma_f32_16x16x32_bf16 v[102:105], v[230:233], v[206:209], v[102:105]
	v_mfma_f32_16x16x32_bf16 v[94:97], v[238:241], v[206:209], v[94:97]
	v_mfma_f32_16x16x32_bf16 v[86:89], v[230:233], v[214:217], v[86:89]
	v_mfma_f32_16x16x32_bf16 v[78:81], v[238:241], v[214:217], v[78:81]
	v_mfma_f32_16x16x32_bf16 v[70:73], v[230:233], v[222:225], v[70:73]
	v_mfma_f32_16x16x32_bf16 v[66:69], v[238:241], v[222:225], v[66:69]
	v_mfma_f32_16x16x32_bf16 v[118:121], v[234:237], v[182:185], v[118:121]
	s_waitcnt lgkmcnt(0)
	v_mfma_f32_16x16x32_bf16 v[110:113], v[242:245], v[182:185], v[110:113]
	v_mfma_f32_16x16x32_bf16 v[102:105], v[234:237], v[210:213], v[102:105]
	v_mfma_f32_16x16x32_bf16 v[94:97], v[242:245], v[210:213], v[94:97]
	v_mfma_f32_16x16x32_bf16 v[86:89], v[234:237], v[218:221], v[86:89]
	v_mfma_f32_16x16x32_bf16 v[78:81], v[242:245], v[218:221], v[78:81]
	v_mfma_f32_16x16x32_bf16 v[70:73], v[234:237], v[226:229], v[70:73]
	v_mfma_f32_16x16x32_bf16 v[66:69], v[242:245], v[226:229], v[66:69]
	s_barrier
	s_mov_b32 m0, s47
	v_lshl_add_u64 v[248:249], s[48:49], 0, v[162:163]
	ds_read_b128 v[172:175], v180 offset:16384
	ds_read_b128 v[182:185], v180 offset:17408
	ds_read_b128 v[206:209], v180 offset:18432
	ds_read_b128 v[210:213], v180 offset:19456
	ds_read_b128 v[214:217], v180 offset:20480
	ds_read_b128 v[218:221], v180 offset:21504
	ds_read_b128 v[222:225], v180 offset:22528
	ds_read_b128 v[226:229], v180 offset:23552
	global_load_lds_dwordx4 v[248:249], off
	s_mov_b32 m0, s50
	v_lshl_add_u64 v[250:251], s[48:49], 0, v[164:165]
	global_load_lds_dwordx4 v[250:251], off
	s_barrier
	s_waitcnt lgkmcnt(7)
	v_mfma_f32_16x16x32_bf16 v[62:65], v[130:133], v[172:175], v[62:65]
	v_mfma_f32_16x16x32_bf16 v[58:61], v[138:141], v[172:175], v[58:61]
	s_waitcnt lgkmcnt(5)
	v_mfma_f32_16x16x32_bf16 v[50:53], v[130:133], v[206:209], v[50:53]
	v_mfma_f32_16x16x32_bf16 v[42:45], v[138:141], v[206:209], v[42:45]
	s_waitcnt lgkmcnt(3)
	v_mfma_f32_16x16x32_bf16 v[34:37], v[130:133], v[214:217], v[34:37]
	v_mfma_f32_16x16x32_bf16 v[26:29], v[138:141], v[214:217], v[26:29]
	s_waitcnt lgkmcnt(1)
	v_mfma_f32_16x16x32_bf16 v[18:21], v[130:133], v[222:225], v[18:21]
	v_mfma_f32_16x16x32_bf16 v[10:13], v[138:141], v[222:225], v[10:13]
	v_mfma_f32_16x16x32_bf16 v[62:65], v[134:137], v[182:185], v[62:65]
	v_mfma_f32_16x16x32_bf16 v[58:61], v[142:145], v[182:185], v[58:61]
	v_mfma_f32_16x16x32_bf16 v[50:53], v[134:137], v[210:213], v[50:53]
	v_mfma_f32_16x16x32_bf16 v[42:45], v[142:145], v[210:213], v[42:45]
	v_mfma_f32_16x16x32_bf16 v[34:37], v[134:137], v[218:221], v[34:37]
	v_mfma_f32_16x16x32_bf16 v[26:29], v[142:145], v[218:221], v[26:29]
	s_waitcnt lgkmcnt(0)
	v_mfma_f32_16x16x32_bf16 v[18:21], v[134:137], v[226:229], v[18:21]
	v_mfma_f32_16x16x32_bf16 v[10:13], v[142:145], v[226:229], v[10:13]
	s_barrier
	s_add_u32 s66, s22, 0x40000
	s_addc_u32 s67, s23, 0
	s_add_i32 s65, s68, s27
	s_mov_b32 m0, s65
	v_lshl_add_u64 v[130:131], s[66:67], 0, v[0:1]
	global_load_lds_dwordx4 v[130:131], off
	s_add_i32 m0, s65, 0x2000
	v_lshl_add_u64 v[130:131], s[66:67], 0, v[166:167]
	global_load_lds_dwordx4 v[130:131], off
	s_waitcnt vmcnt(6)
	s_barrier
	v_mfma_f32_16x16x32_bf16 v[54:57], v[230:233], v[172:175], v[54:57]
	v_mfma_f32_16x16x32_bf16 v[46:49], v[238:241], v[172:175], v[46:49]
	v_mfma_f32_16x16x32_bf16 v[38:41], v[230:233], v[206:209], v[38:41]
	v_mfma_f32_16x16x32_bf16 v[30:33], v[238:241], v[206:209], v[30:33]
	v_mfma_f32_16x16x32_bf16 v[22:25], v[230:233], v[214:217], v[22:25]
	v_mfma_f32_16x16x32_bf16 v[14:17], v[238:241], v[214:217], v[14:17]
	v_mfma_f32_16x16x32_bf16 v[6:9], v[230:233], v[222:225], v[6:9]
	v_mfma_f32_16x16x32_bf16 v[2:5], v[238:241], v[222:225], v[2:5]
	v_mfma_f32_16x16x32_bf16 v[54:57], v[234:237], v[182:185], v[54:57]
	v_mfma_f32_16x16x32_bf16 v[46:49], v[242:245], v[182:185], v[46:49]
	v_mfma_f32_16x16x32_bf16 v[38:41], v[234:237], v[210:213], v[38:41]
	v_mfma_f32_16x16x32_bf16 v[30:33], v[242:245], v[210:213], v[30:33]
	v_mfma_f32_16x16x32_bf16 v[22:25], v[234:237], v[218:221], v[22:25]
	v_mfma_f32_16x16x32_bf16 v[14:17], v[242:245], v[218:221], v[14:17]
	v_mfma_f32_16x16x32_bf16 v[6:9], v[234:237], v[226:229], v[6:9]
	v_mfma_f32_16x16x32_bf16 v[2:5], v[242:245], v[226:229], v[2:5]
	s_barrier
	s_add_i32 s65, 0, 0x18000
	v_add_u32_e32 v142, s65, v178
	ds_read_b128 v[130:133], v142
	ds_read_b128 v[134:137], v142 offset:1024
	ds_read_b128 v[138:141], v142 offset:2048
	ds_read_b128 v[142:145], v142 offset:3072
	s_add_u32 s48, s48, 0x40000
	s_addc_u32 s49, s49, 0
	s_mov_b32 m0, s51
	v_lshl_add_u64 v[230:231], s[48:49], 0, v[162:163]
	ds_read_b128 v[172:175], v180 offset:32768
	ds_read_b128 v[182:185], v180 offset:33792
	ds_read_b128 v[206:209], v180 offset:34816
	ds_read_b128 v[210:213], v180 offset:35840
	ds_read_b128 v[214:217], v180 offset:36864
	ds_read_b128 v[218:221], v180 offset:37888
	ds_read_b128 v[222:225], v180 offset:38912
	ds_read_b128 v[226:229], v180 offset:39936
	global_load_lds_dwordx4 v[230:231], off
	s_mov_b32 m0, s54
	v_lshl_add_u64 v[230:231], s[48:49], 0, v[164:165]
	global_load_lds_dwordx4 v[230:231], off
	s_waitcnt lgkmcnt(8)
	s_barrier
	s_waitcnt lgkmcnt(7)
	v_mfma_f32_16x16x32_bf16 v[126:129], v[130:133], v[172:175], v[126:129]
	v_mfma_f32_16x16x32_bf16 v[122:125], v[138:141], v[172:175], v[122:125]
	s_waitcnt lgkmcnt(5)
	v_mfma_f32_16x16x32_bf16 v[114:117], v[130:133], v[206:209], v[114:117]
	v_mfma_f32_16x16x32_bf16 v[106:109], v[138:141], v[206:209], v[106:109]
	s_waitcnt lgkmcnt(3)
	v_mfma_f32_16x16x32_bf16 v[98:101], v[130:133], v[214:217], v[98:101]
	v_mfma_f32_16x16x32_bf16 v[90:93], v[138:141], v[214:217], v[90:93]
	s_waitcnt lgkmcnt(1)
	v_mfma_f32_16x16x32_bf16 v[82:85], v[130:133], v[222:225], v[82:85]
	v_mfma_f32_16x16x32_bf16 v[74:77], v[138:141], v[222:225], v[74:77]
	v_mfma_f32_16x16x32_bf16 v[126:129], v[134:137], v[182:185], v[126:129]
	v_mfma_f32_16x16x32_bf16 v[122:125], v[142:145], v[182:185], v[122:125]
	v_mfma_f32_16x16x32_bf16 v[114:117], v[134:137], v[210:213], v[114:117]
	v_mfma_f32_16x16x32_bf16 v[106:109], v[142:145], v[210:213], v[106:109]
	v_mfma_f32_16x16x32_bf16 v[98:101], v[134:137], v[218:221], v[98:101]
	v_mfma_f32_16x16x32_bf16 v[90:93], v[142:145], v[218:221], v[90:93]
	s_waitcnt lgkmcnt(0)
	v_mfma_f32_16x16x32_bf16 v[82:85], v[134:137], v[226:229], v[82:85]
	v_mfma_f32_16x16x32_bf16 v[74:77], v[142:145], v[226:229], v[74:77]
	s_barrier
	s_add_i32 s48, 0, 0x1c000
	s_add_i32 s49, s65, s27
	v_add_u32_e32 v181, s48, v178
	v_lshl_add_u64 v[186:187], v[186:187], 0, s[94:95]
	s_mov_b32 m0, s49
	ds_read_b128 v[230:233], v181
	ds_read_b128 v[234:237], v181 offset:1024
	ds_read_b128 v[238:241], v181 offset:2048
	ds_read_b128 v[242:245], v181 offset:3072
	global_load_lds_dwordx4 v[186:187], off
	s_add_i32 m0, s49, 0x2000
	v_lshl_add_u64 v[186:187], v[246:247], 0, s[94:95]
	global_load_lds_dwordx4 v[186:187], off
	s_barrier
	s_waitcnt lgkmcnt(3)
	v_mfma_f32_16x16x32_bf16 v[118:121], v[230:233], v[172:175], v[118:121]
	s_waitcnt lgkmcnt(1)
	v_mfma_f32_16x16x32_bf16 v[110:113], v[238:241], v[172:175], v[110:113]
	v_mfma_f32_16x16x32_bf16 v[102:105], v[230:233], v[206:209], v[102:105]
	v_mfma_f32_16x16x32_bf16 v[94:97], v[238:241], v[206:209], v[94:97]
	v_mfma_f32_16x16x32_bf16 v[86:89], v[230:233], v[214:217], v[86:89]
	v_mfma_f32_16x16x32_bf16 v[78:81], v[238:241], v[214:217], v[78:81]
	v_mfma_f32_16x16x32_bf16 v[70:73], v[230:233], v[222:225], v[70:73]
	v_mfma_f32_16x16x32_bf16 v[66:69], v[238:241], v[222:225], v[66:69]
	v_mfma_f32_16x16x32_bf16 v[118:121], v[234:237], v[182:185], v[118:121]
	s_waitcnt lgkmcnt(0)
	v_mfma_f32_16x16x32_bf16 v[110:113], v[242:245], v[182:185], v[110:113]
	v_mfma_f32_16x16x32_bf16 v[102:105], v[234:237], v[210:213], v[102:105]
	v_mfma_f32_16x16x32_bf16 v[94:97], v[242:245], v[210:213], v[94:97]
	v_mfma_f32_16x16x32_bf16 v[86:89], v[234:237], v[218:221], v[86:89]
	v_mfma_f32_16x16x32_bf16 v[78:81], v[242:245], v[218:221], v[78:81]
	v_mfma_f32_16x16x32_bf16 v[70:73], v[234:237], v[226:229], v[70:73]
	v_mfma_f32_16x16x32_bf16 v[66:69], v[242:245], v[226:229], v[66:69]
	s_barrier
	s_mov_b32 m0, s55
	v_lshl_add_u64 v[186:187], v[248:249], 0, s[94:95]
	ds_read_b128 v[172:175], v180 offset:49152
	ds_read_b128 v[182:185], v180 offset:50176
	ds_read_b128 v[206:209], v180 offset:51200
	ds_read_b128 v[210:213], v180 offset:52224
	ds_read_b128 v[214:217], v180 offset:53248
	ds_read_b128 v[218:221], v180 offset:54272
	ds_read_b128 v[222:225], v180 offset:55296
	ds_read_b128 v[226:229], v180 offset:56320
	global_load_lds_dwordx4 v[186:187], off
	s_mov_b32 m0, s56
	v_lshl_add_u64 v[186:187], v[250:251], 0, s[94:95]
	global_load_lds_dwordx4 v[186:187], off
	s_barrier
	s_waitcnt lgkmcnt(7)
	v_mfma_f32_16x16x32_bf16 v[62:65], v[130:133], v[172:175], v[62:65]
	v_mfma_f32_16x16x32_bf16 v[58:61], v[138:141], v[172:175], v[58:61]
	s_waitcnt lgkmcnt(5)
	v_mfma_f32_16x16x32_bf16 v[50:53], v[130:133], v[206:209], v[50:53]
	v_mfma_f32_16x16x32_bf16 v[42:45], v[138:141], v[206:209], v[42:45]
	s_waitcnt lgkmcnt(3)
	v_mfma_f32_16x16x32_bf16 v[34:37], v[130:133], v[214:217], v[34:37]
	v_mfma_f32_16x16x32_bf16 v[26:29], v[138:141], v[214:217], v[26:29]
	s_waitcnt lgkmcnt(1)
	v_mfma_f32_16x16x32_bf16 v[18:21], v[130:133], v[222:225], v[18:21]
	v_mfma_f32_16x16x32_bf16 v[10:13], v[138:141], v[222:225], v[10:13]
	v_mfma_f32_16x16x32_bf16 v[62:65], v[134:137], v[182:185], v[62:65]
	v_mfma_f32_16x16x32_bf16 v[58:61], v[142:145], v[182:185], v[58:61]
	v_mfma_f32_16x16x32_bf16 v[50:53], v[134:137], v[210:213], v[50:53]
	v_mfma_f32_16x16x32_bf16 v[42:45], v[142:145], v[210:213], v[42:45]
	v_mfma_f32_16x16x32_bf16 v[34:37], v[134:137], v[218:221], v[34:37]
	v_mfma_f32_16x16x32_bf16 v[26:29], v[142:145], v[218:221], v[26:29]
	s_waitcnt lgkmcnt(0)
	v_mfma_f32_16x16x32_bf16 v[18:21], v[134:137], v[226:229], v[18:21]
	v_mfma_f32_16x16x32_bf16 v[10:13], v[142:145], v[226:229], v[10:13]
	s_barrier
	s_add_u32 s22, s22, 0x40080
	s_addc_u32 s23, s23, 0
	s_add_i32 s48, s48, s27
	s_mov_b32 m0, s48
	v_lshl_add_u64 v[130:131], s[22:23], 0, v[0:1]
	global_load_lds_dwordx4 v[130:131], off
	s_add_i32 m0, s48, 0x2000
	v_lshl_add_u64 v[130:131], s[22:23], 0, v[166:167]
	global_load_lds_dwordx4 v[130:131], off
	s_waitcnt vmcnt(6)
	s_barrier
	v_mfma_f32_16x16x32_bf16 v[54:57], v[230:233], v[172:175], v[54:57]
	v_mfma_f32_16x16x32_bf16 v[46:49], v[238:241], v[172:175], v[46:49]
	v_mfma_f32_16x16x32_bf16 v[38:41], v[230:233], v[206:209], v[38:41]
	v_mfma_f32_16x16x32_bf16 v[30:33], v[238:241], v[206:209], v[30:33]
	v_mfma_f32_16x16x32_bf16 v[22:25], v[230:233], v[214:217], v[22:25]
	v_mfma_f32_16x16x32_bf16 v[14:17], v[238:241], v[214:217], v[14:17]
	v_mfma_f32_16x16x32_bf16 v[6:9], v[230:233], v[222:225], v[6:9]
	v_mfma_f32_16x16x32_bf16 v[2:5], v[238:241], v[222:225], v[2:5]
	v_mfma_f32_16x16x32_bf16 v[54:57], v[234:237], v[182:185], v[54:57]
	v_mfma_f32_16x16x32_bf16 v[46:49], v[242:245], v[182:185], v[46:49]
	v_mfma_f32_16x16x32_bf16 v[38:41], v[234:237], v[210:213], v[38:41]
	v_mfma_f32_16x16x32_bf16 v[30:33], v[242:245], v[210:213], v[30:33]
	v_mfma_f32_16x16x32_bf16 v[22:25], v[234:237], v[218:221], v[22:25]
	v_mfma_f32_16x16x32_bf16 v[14:17], v[242:245], v[218:221], v[14:17]
	v_mfma_f32_16x16x32_bf16 v[6:9], v[234:237], v[226:229], v[6:9]
	v_mfma_f32_16x16x32_bf16 v[2:5], v[242:245], v[226:229], v[2:5]
	s_barrier
	s_add_i32 s64, s64, 2
	s_add_u32 s0, s0, 0x100
	s_addc_u32 s1, s1, 0
	s_add_u32 s62, s62, 0x100
	s_addc_u32 s63, s63, 0
	s_cmp_gt_u32 s64, 13
	s_cbranch_scc0 .LBB0_57
	v_lshl_or_b32 v172, s59, 8, v179
	v_ashrrev_i32_e32 v173, 31, v172
	v_cndmask_b32_e64 v131, 0, 1, s[2:3]
	v_lshl_add_u64 v[174:175], v[172:173], 2, s[8:9]
	v_mov_b32_e32 v130, 0
	v_cmp_ne_u32_e64 s[0:1], 1, v131
	s_andn2_b64 vcc, exec, s[2:3]
	v_mov_b32_e32 v134, 0
	v_mov_b32_e32 v135, 0
	v_mov_b32_e32 v136, 0
	v_mov_b32_e32 v137, 0
	s_cbranch_vccnz .LBB0_60
	global_load_dwordx4 v[134:137], v[174:175], off

.Lkprio_4:
.LBB0_95:
	s_add_u32 s22, s8, 0xfffc0080
	s_addc_u32 s23, s9, -1
	s_add_i32 s63, 0, 0x10000
	v_add_u32_e32 v78, s63, v178
	ds_read_b128 v[58:61], v78
	ds_read_b128 v[66:69], v78 offset:1024
	ds_read_b128 v[74:77], v78 offset:2048
	ds_read_b128 v[78:81], v78 offset:3072
	s_cmp_eq_u32 s49, 12
	s_cselect_b32 s29, s25, s23
	s_cselect_b32 s28, s26, s22
	s_cselect_b32 s23, s27, s47
	s_cselect_b32 s22, s30, s31
	v_lshl_add_u64 v[186:187], s[8:9], 0, v[168:169]
	s_add_i32 m0, s3, 0xc000
	ds_read_b128 v[172:175], v180
	ds_read_b128 v[182:185], v180 offset:1024
	ds_read_b128 v[206:209], v180 offset:2048
	ds_read_b128 v[210:213], v180 offset:3072
	ds_read_b128 v[214:217], v180 offset:4096
	ds_read_b128 v[218:221], v180 offset:5120
	ds_read_b128 v[222:225], v180 offset:6144
	ds_read_b128 v[226:229], v180 offset:7168
	global_load_lds_dwordx4 v[186:187], off
	s_add_i32 m0, s3, 0xe000
	v_lshl_add_u64 v[186:187], s[8:9], 0, v[170:171]
	global_load_lds_dwordx4 v[186:187], off
	s_waitcnt lgkmcnt(8)
	s_barrier
	s_waitcnt lgkmcnt(7)
	v_mfma_f32_16x16x32_bf16 v[142:145], v[58:61], v[172:175], v[142:145]
	v_mfma_f32_16x16x32_bf16 v[138:141], v[74:77], v[172:175], v[138:141]
	s_waitcnt lgkmcnt(5)
	v_mfma_f32_16x16x32_bf16 v[126:129], v[58:61], v[206:209], v[126:129]
	v_mfma_f32_16x16x32_bf16 v[118:121], v[74:77], v[206:209], v[118:121]
	s_waitcnt lgkmcnt(3)
	v_mfma_f32_16x16x32_bf16 v[110:113], v[58:61], v[214:217], v[110:113]
	v_mfma_f32_16x16x32_bf16 v[102:105], v[74:77], v[214:217], v[102:105]
	s_waitcnt lgkmcnt(1)
	v_mfma_f32_16x16x32_bf16 v[94:97], v[58:61], v[222:225], v[94:97]
	v_mfma_f32_16x16x32_bf16 v[86:89], v[74:77], v[222:225], v[86:89]
	v_mfma_f32_16x16x32_bf16 v[142:145], v[66:69], v[182:185], v[142:145]
	v_mfma_f32_16x16x32_bf16 v[138:141], v[78:81], v[182:185], v[138:141]
	v_mfma_f32_16x16x32_bf16 v[126:129], v[66:69], v[210:213], v[126:129]
	v_mfma_f32_16x16x32_bf16 v[118:121], v[78:81], v[210:213], v[118:121]
	v_mfma_f32_16x16x32_bf16 v[110:113], v[66:69], v[218:221], v[110:113]
	v_mfma_f32_16x16x32_bf16 v[102:105], v[78:81], v[218:221], v[102:105]
	s_waitcnt lgkmcnt(0)
	v_mfma_f32_16x16x32_bf16 v[94:97], v[66:69], v[226:229], v[94:97]
	v_mfma_f32_16x16x32_bf16 v[86:89], v[78:81], v[226:229], v[86:89]
	s_barrier
	s_add_i32 s66, 0, 0x14000
	s_add_i32 s63, s63, s37
	v_add_u32_e32 v181, s66, v178
	v_lshl_add_u64 v[186:187], s[22:23], 0, v[0:1]
	s_mov_b32 m0, s63
	ds_read_b128 v[230:233], v181
	ds_read_b128 v[234:237], v181 offset:1024
	ds_read_b128 v[238:241], v181 offset:2048
	ds_read_b128 v[242:245], v181 offset:3072
	global_load_lds_dwordx4 v[186:187], off
	s_add_i32 m0, s63, 0x2000
	v_lshl_add_u64 v[246:247], s[22:23], 0, v[166:167]
	global_load_lds_dwordx4 v[246:247], off
	s_barrier
	s_waitcnt lgkmcnt(3)
	v_mfma_f32_16x16x32_bf16 v[134:137], v[230:233], v[172:175], v[134:137]
	s_waitcnt lgkmcnt(1)
	v_mfma_f32_16x16x32_bf16 v[130:133], v[238:241], v[172:175], v[130:133]
	v_mfma_f32_16x16x32_bf16 v[122:125], v[230:233], v[206:209], v[122:125]
	v_mfma_f32_16x16x32_bf16 v[114:117], v[238:241], v[206:209], v[114:117]
	v_mfma_f32_16x16x32_bf16 v[106:109], v[230:233], v[214:217], v[106:109]
	v_mfma_f32_16x16x32_bf16 v[98:101], v[238:241], v[214:217], v[98:101]
	v_mfma_f32_16x16x32_bf16 v[90:93], v[230:233], v[222:225], v[90:93]
	v_mfma_f32_16x16x32_bf16 v[82:85], v[238:241], v[222:225], v[82:85]
	v_mfma_f32_16x16x32_bf16 v[134:137], v[234:237], v[182:185], v[134:137]
	s_waitcnt lgkmcnt(0)
	v_mfma_f32_16x16x32_bf16 v[130:133], v[242:245], v[182:185], v[130:133]
	v_mfma_f32_16x16x32_bf16 v[122:125], v[234:237], v[210:213], v[122:125]
	v_mfma_f32_16x16x32_bf16 v[114:117], v[242:245], v[210:213], v[114:117]
	v_mfma_f32_16x16x32_bf16 v[106:109], v[234:237], v[218:221], v[106:109]
	v_mfma_f32_16x16x32_bf16 v[98:101], v[242:245], v[218:221], v[98:101]
	v_mfma_f32_16x16x32_bf16 v[90:93], v[234:237], v[226:229], v[90:93]
	v_mfma_f32_16x16x32_bf16 v[82:85], v[242:245], v[226:229], v[82:85]
	s_barrier
	s_mov_b32 m0, s3
	v_lshl_add_u64 v[248:249], s[28:29], 0, v[162:163]
	ds_read_b128 v[172:175], v180 offset:16384
	ds_read_b128 v[182:185], v180 offset:17408
	ds_read_b128 v[206:209], v180 offset:18432
	ds_read_b128 v[210:213], v180 offset:19456
	ds_read_b128 v[214:217], v180 offset:20480
	ds_read_b128 v[218:221], v180 offset:21504
	ds_read_b128 v[222:225], v180 offset:22528
	ds_read_b128 v[226:229], v180 offset:23552
	global_load_lds_dwordx4 v[248:249], off
	s_mov_b32 m0, s56
	v_lshl_add_u64 v[250:251], s[28:29], 0, v[164:165]
	global_load_lds_dwordx4 v[250:251], off
	s_barrier
	s_waitcnt lgkmcnt(7)
	v_mfma_f32_16x16x32_bf16 v[70:73], v[58:61], v[172:175], v[70:73]
	v_mfma_f32_16x16x32_bf16 v[54:57], v[74:77], v[172:175], v[54:57]
	s_waitcnt lgkmcnt(5)
	v_mfma_f32_16x16x32_bf16 v[46:49], v[58:61], v[206:209], v[46:49]
	v_mfma_f32_16x16x32_bf16 v[38:41], v[74:77], v[206:209], v[38:41]
	s_waitcnt lgkmcnt(3)
	v_mfma_f32_16x16x32_bf16 v[30:33], v[58:61], v[214:217], v[30:33]
	v_mfma_f32_16x16x32_bf16 v[22:25], v[74:77], v[214:217], v[22:25]
	s_waitcnt lgkmcnt(1)
	v_mfma_f32_16x16x32_bf16 v[14:17], v[58:61], v[222:225], v[14:17]
	v_mfma_f32_16x16x32_bf16 v[6:9], v[74:77], v[222:225], v[6:9]
	v_mfma_f32_16x16x32_bf16 v[70:73], v[66:69], v[182:185], v[70:73]
	v_mfma_f32_16x16x32_bf16 v[54:57], v[78:81], v[182:185], v[54:57]
	v_mfma_f32_16x16x32_bf16 v[46:49], v[66:69], v[210:213], v[46:49]
	v_mfma_f32_16x16x32_bf16 v[38:41], v[78:81], v[210:213], v[38:41]
	v_mfma_f32_16x16x32_bf16 v[30:33], v[66:69], v[218:221], v[30:33]
	v_mfma_f32_16x16x32_bf16 v[22:25], v[78:81], v[218:221], v[22:25]
	s_waitcnt lgkmcnt(0)
	v_mfma_f32_16x16x32_bf16 v[14:17], v[66:69], v[226:229], v[14:17]
	v_mfma_f32_16x16x32_bf16 v[6:9], v[78:81], v[226:229], v[6:9]
	s_barrier
	s_add_u32 s64, s22, 0x40000
	s_addc_u32 s65, s23, 0
	s_add_i32 s63, s66, s37
	s_mov_b32 m0, s63
	v_lshl_add_u64 v[58:59], s[64:65], 0, v[0:1]
	global_load_lds_dwordx4 v[58:59], off
	s_add_i32 m0, s63, 0x2000
	v_lshl_add_u64 v[58:59], s[64:65], 0, v[166:167]
	global_load_lds_dwordx4 v[58:59], off
	s_waitcnt vmcnt(6)
	s_barrier
	v_mfma_f32_16x16x32_bf16 v[50:53], v[238:241], v[172:175], v[50:53]
	v_mfma_f32_16x16x32_bf16 v[42:45], v[230:233], v[206:209], v[42:45]
	v_mfma_f32_16x16x32_bf16 v[34:37], v[238:241], v[206:209], v[34:37]
	v_mfma_f32_16x16x32_bf16 v[26:29], v[230:233], v[214:217], v[26:29]
	v_mfma_f32_16x16x32_bf16 v[18:21], v[238:241], v[214:217], v[18:21]
	v_mfma_f32_16x16x32_bf16 v[10:13], v[230:233], v[222:225], v[10:13]
	v_mfma_f32_16x16x32_bf16 v[2:5], v[238:241], v[222:225], v[2:5]
	v_mfma_f32_16x16x32_bf16 v[58:61], v[230:233], v[172:175], v[62:65]
	v_mfma_f32_16x16x32_bf16 v[50:53], v[242:245], v[182:185], v[50:53]
	v_mfma_f32_16x16x32_bf16 v[42:45], v[234:237], v[210:213], v[42:45]
	v_mfma_f32_16x16x32_bf16 v[34:37], v[242:245], v[210:213], v[34:37]
	v_mfma_f32_16x16x32_bf16 v[26:29], v[234:237], v[218:221], v[26:29]
	v_mfma_f32_16x16x32_bf16 v[18:21], v[242:245], v[218:221], v[18:21]
	v_mfma_f32_16x16x32_bf16 v[10:13], v[234:237], v[226:229], v[10:13]
	v_mfma_f32_16x16x32_bf16 v[2:5], v[242:245], v[226:229], v[2:5]
	v_mfma_f32_16x16x32_bf16 v[58:61], v[234:237], v[182:185], v[58:61]
	s_barrier
	s_add_i32 s63, 0, 0x18000
	v_add_u32_e32 v78, s63, v178
	ds_read_b128 v[62:65], v78
	ds_read_b128 v[66:69], v78 offset:1024
	ds_read_b128 v[74:77], v78 offset:2048
	ds_read_b128 v[78:81], v78 offset:3072
	s_add_u32 s28, s28, 0x40000
	s_addc_u32 s29, s29, 0
	s_mov_b32 m0, s57
	v_lshl_add_u64 v[230:231], s[28:29], 0, v[162:163]
	ds_read_b128 v[172:175], v180 offset:32768
	ds_read_b128 v[182:185], v180 offset:33792
	ds_read_b128 v[206:209], v180 offset:34816
	ds_read_b128 v[210:213], v180 offset:35840
	ds_read_b128 v[214:217], v180 offset:36864
	ds_read_b128 v[218:221], v180 offset:37888
	ds_read_b128 v[222:225], v180 offset:38912
	ds_read_b128 v[226:229], v180 offset:39936
	global_load_lds_dwordx4 v[230:231], off
	s_mov_b32 m0, s58
	v_lshl_add_u64 v[230:231], s[28:29], 0, v[164:165]
	global_load_lds_dwordx4 v[230:231], off
	s_waitcnt lgkmcnt(8)
	s_barrier
	s_waitcnt lgkmcnt(7)
	v_mfma_f32_16x16x32_bf16 v[142:145], v[62:65], v[172:175], v[142:145]
	v_mfma_f32_16x16x32_bf16 v[138:141], v[74:77], v[172:175], v[138:141]
	s_waitcnt lgkmcnt(5)
	v_mfma_f32_16x16x32_bf16 v[126:129], v[62:65], v[206:209], v[126:129]
	v_mfma_f32_16x16x32_bf16 v[118:121], v[74:77], v[206:209], v[118:121]
	s_waitcnt lgkmcnt(3)
	v_mfma_f32_16x16x32_bf16 v[110:113], v[62:65], v[214:217], v[110:113]
	v_mfma_f32_16x16x32_bf16 v[102:105], v[74:77], v[214:217], v[102:105]
	s_waitcnt lgkmcnt(1)
	v_mfma_f32_16x16x32_bf16 v[94:97], v[62:65], v[222:225], v[94:97]
	v_mfma_f32_16x16x32_bf16 v[86:89], v[74:77], v[222:225], v[86:89]
	v_mfma_f32_16x16x32_bf16 v[142:145], v[66:69], v[182:185], v[142:145]
	v_mfma_f32_16x16x32_bf16 v[138:141], v[78:81], v[182:185], v[138:141]
	v_mfma_f32_16x16x32_bf16 v[126:129], v[66:69], v[210:213], v[126:129]
	v_mfma_f32_16x16x32_bf16 v[118:121], v[78:81], v[210:213], v[118:121]
	v_mfma_f32_16x16x32_bf16 v[110:113], v[66:69], v[218:221], v[110:113]
	v_mfma_f32_16x16x32_bf16 v[102:105], v[78:81], v[218:221], v[102:105]
	s_waitcnt lgkmcnt(0)
	v_mfma_f32_16x16x32_bf16 v[94:97], v[66:69], v[226:229], v[94:97]
	v_mfma_f32_16x16x32_bf16 v[86:89], v[78:81], v[226:229], v[86:89]
	s_barrier
	s_add_i32 s28, 0, 0x1c000
	s_add_i32 s29, s63, s37
	v_add_u32_e32 v181, s28, v178
	v_lshl_add_u64 v[186:187], v[186:187], 0, s[94:95]
	s_mov_b32 m0, s29
	ds_read_b128 v[230:233], v181
	ds_read_b128 v[234:237], v181 offset:1024
	ds_read_b128 v[238:241], v181 offset:2048
	ds_read_b128 v[242:245], v181 offset:3072
	global_load_lds_dwordx4 v[186:187], off
	s_add_i32 m0, s29, 0x2000
	v_lshl_add_u64 v[186:187], v[246:247], 0, s[94:95]
	global_load_lds_dwordx4 v[186:187], off
	s_barrier
	s_waitcnt lgkmcnt(3)
	v_mfma_f32_16x16x32_bf16 v[134:137], v[230:233], v[172:175], v[134:137]
	s_waitcnt lgkmcnt(1)
	v_mfma_f32_16x16x32_bf16 v[130:133], v[238:241], v[172:175], v[130:133]
	v_mfma_f32_16x16x32_bf16 v[122:125], v[230:233], v[206:209], v[122:125]
	v_mfma_f32_16x16x32_bf16 v[114:117], v[238:241], v[206:209], v[114:117]
	v_mfma_f32_16x16x32_bf16 v[106:109], v[230:233], v[214:217], v[106:109]
	v_mfma_f32_16x16x32_bf16 v[98:101], v[238:241], v[214:217], v[98:101]
	v_mfma_f32_16x16x32_bf16 v[90:93], v[230:233], v[222:225], v[90:93]
	v_mfma_f32_16x16x32_bf16 v[82:85], v[238:241], v[222:225], v[82:85]
	v_mfma_f32_16x16x32_bf16 v[134:137], v[234:237], v[182:185], v[134:137]
	s_waitcnt lgkmcnt(0)
	v_mfma_f32_16x16x32_bf16 v[130:133], v[242:245], v[182:185], v[130:133]
	v_mfma_f32_16x16x32_bf16 v[122:125], v[234:237], v[210:213], v[122:125]
	v_mfma_f32_16x16x32_bf16 v[114:117], v[242:245], v[210:213], v[114:117]
	v_mfma_f32_16x16x32_bf16 v[106:109], v[234:237], v[218:221], v[106:109]
	v_mfma_f32_16x16x32_bf16 v[98:101], v[242:245], v[218:221], v[98:101]
	v_mfma_f32_16x16x32_bf16 v[90:93], v[234:237], v[226:229], v[90:93]
	v_mfma_f32_16x16x32_bf16 v[82:85], v[242:245], v[226:229], v[82:85]
	s_barrier
	s_mov_b32 m0, s59
	v_lshl_add_u64 v[186:187], v[248:249], 0, s[94:95]
	ds_read_b128 v[172:175], v180 offset:49152
	ds_read_b128 v[182:185], v180 offset:50176
	ds_read_b128 v[206:209], v180 offset:51200
	ds_read_b128 v[210:213], v180 offset:52224
	ds_read_b128 v[214:217], v180 offset:53248
	ds_read_b128 v[218:221], v180 offset:54272
	ds_read_b128 v[222:225], v180 offset:55296
	ds_read_b128 v[226:229], v180 offset:56320
	global_load_lds_dwordx4 v[186:187], off
	s_mov_b32 m0, s60
	v_lshl_add_u64 v[186:187], v[250:251], 0, s[94:95]
	global_load_lds_dwordx4 v[186:187], off
	s_barrier
	s_waitcnt lgkmcnt(7)
	v_mfma_f32_16x16x32_bf16 v[70:73], v[62:65], v[172:175], v[70:73]
	v_mfma_f32_16x16x32_bf16 v[54:57], v[74:77], v[172:175], v[54:57]
	s_waitcnt lgkmcnt(5)
	v_mfma_f32_16x16x32_bf16 v[46:49], v[62:65], v[206:209], v[46:49]
	v_mfma_f32_16x16x32_bf16 v[38:41], v[74:77], v[206:209], v[38:41]
	s_waitcnt lgkmcnt(3)
	v_mfma_f32_16x16x32_bf16 v[30:33], v[62:65], v[214:217], v[30:33]
	v_mfma_f32_16x16x32_bf16 v[22:25], v[74:77], v[214:217], v[22:25]
	s_waitcnt lgkmcnt(1)
	v_mfma_f32_16x16x32_bf16 v[14:17], v[62:65], v[222:225], v[14:17]
	v_mfma_f32_16x16x32_bf16 v[6:9], v[74:77], v[222:225], v[6:9]
	v_mfma_f32_16x16x32_bf16 v[70:73], v[66:69], v[182:185], v[70:73]
	v_mfma_f32_16x16x32_bf16 v[54:57], v[78:81], v[182:185], v[54:57]
	v_mfma_f32_16x16x32_bf16 v[46:49], v[66:69], v[210:213], v[46:49]
	v_mfma_f32_16x16x32_bf16 v[38:41], v[78:81], v[210:213], v[38:41]
	v_mfma_f32_16x16x32_bf16 v[30:33], v[66:69], v[218:221], v[30:33]
	v_mfma_f32_16x16x32_bf16 v[22:25], v[78:81], v[218:221], v[22:25]
	s_waitcnt lgkmcnt(0)
	v_mfma_f32_16x16x32_bf16 v[14:17], v[66:69], v[226:229], v[14:17]
	v_mfma_f32_16x16x32_bf16 v[6:9], v[78:81], v[226:229], v[6:9]
	s_barrier
	s_add_u32 s22, s22, 0x40080
	s_addc_u32 s23, s23, 0
	s_add_i32 s28, s28, s37
	s_mov_b32 m0, s28
	v_lshl_add_u64 v[62:63], s[22:23], 0, v[0:1]
	global_load_lds_dwordx4 v[62:63], off
	s_add_i32 m0, s28, 0x2000
	v_lshl_add_u64 v[62:63], s[22:23], 0, v[166:167]
	global_load_lds_dwordx4 v[62:63], off
	s_waitcnt vmcnt(6)
	s_barrier
	v_mfma_f32_16x16x32_bf16 v[58:61], v[230:233], v[172:175], v[58:61]
	v_mfma_f32_16x16x32_bf16 v[50:53], v[238:241], v[172:175], v[50:53]
	v_mfma_f32_16x16x32_bf16 v[42:45], v[230:233], v[206:209], v[42:45]
	v_mfma_f32_16x16x32_bf16 v[34:37], v[238:241], v[206:209], v[34:37]
	v_mfma_f32_16x16x32_bf16 v[26:29], v[230:233], v[214:217], v[26:29]
	v_mfma_f32_16x16x32_bf16 v[18:21], v[238:241], v[214:217], v[18:21]
	v_mfma_f32_16x16x32_bf16 v[10:13], v[230:233], v[222:225], v[10:13]
	v_mfma_f32_16x16x32_bf16 v[2:5], v[238:241], v[222:225], v[2:5]
	v_mfma_f32_16x16x32_bf16 v[62:65], v[234:237], v[182:185], v[58:61]
	v_mfma_f32_16x16x32_bf16 v[50:53], v[242:245], v[182:185], v[50:53]
	v_mfma_f32_16x16x32_bf16 v[42:45], v[234:237], v[210:213], v[42:45]
	v_mfma_f32_16x16x32_bf16 v[34:37], v[242:245], v[210:213], v[34:37]
	v_mfma_f32_16x16x32_bf16 v[26:29], v[234:237], v[218:221], v[26:29]
	v_mfma_f32_16x16x32_bf16 v[18:21], v[242:245], v[218:221], v[18:21]
	v_mfma_f32_16x16x32_bf16 v[10:13], v[234:237], v[226:229], v[10:13]
	v_mfma_f32_16x16x32_bf16 v[2:5], v[242:245], v[226:229], v[2:5]
	s_barrier
	s_add_i32 s49, s49, 2
	s_add_u32 s8, s8, 0x100
	s_addc_u32 s9, s9, 0
	s_add_u32 s31, s31, 0x100
	s_addc_u32 s47, s47, 0
	s_cmp_gt_u32 s49, 13
	s_cbranch_scc0 .LBB0_95
	v_lshl_or_b32 v172, s24, 7, v179
	v_ashrrev_i32_e32 v173, 31, v172
	v_lshlrev_b64 v[58:59], 2, v[172:173]
	v_lshl_add_u64 v[60:61], s[40:41], 0, v[58:59]
	v_lshl_add_u64 v[74:75], s[44:45], 0, v[58:59]
	global_load_dwordx4 v[66:69], v[60:61], off offset:16
	global_load_dwordx4 v[78:81], v[60:61], off
	s_nop 0
	global_load_dwordx4 v[58:61], v[74:75], off offset:16
	s_nop 0
	global_load_dwordx4 v[74:77], v[74:75], off
	v_lshl_add_u32 v174, s2, 8, v177
	v_ashrrev_i32_e32 v175, 31, v174
	v_lshl_add_u64 v[172:173], v[172:173], 1, s[20:21]
	v_lshlrev_b64 v[182:183], 11, v[174:175]
	s_mov_b32 s2, 0x50000
	s_mov_b32 s24, s46
	s_mov_b64 s[22:23], s[54:55]
	s_mov_b64 s[8:9], s[50:51]
	s_waitcnt vmcnt(0)
	v_add_f32_e32 v138, v138, v66
	v_add_f32_e32 v126, v126, v78
	v_add_f32_e32 v130, v130, v58
	v_mul_f32_e32 v130, 0xbfb8aa3b, v130
	v_add_f32_e32 v131, v131, v59
	v_add_f32_e32 v122, v122, v74
	v_exp_f32_e32 v130, v130
	v_mul_f32_e32 v131, 0xbfb8aa3b, v131
	v_mul_f32_e32 v122, 0xbfb8aa3b, v122
	v_add_f32_e32 v123, v123, v75
	v_exp_f32_e32 v131, v131
	v_exp_f32_e32 v122, v122
	v_mul_f32_e32 v123, 0xbfb8aa3b, v123
	v_add_f32_e32 v124, v124, v76
	v_exp_f32_e32 v123, v123
	v_mul_f32_e32 v124, 0xbfb8aa3b, v124
	v_add_f32_e32 v125, v125, v77
	v_add_f32_e32 v114, v114, v58
	v_exp_f32_e32 v124, v124
	v_mul_f32_e32 v125, 0xbfb8aa3b, v125
	v_mul_f32_e32 v114, 0xbfb8aa3b, v114
	v_add_f32_e32 v115, v115, v59
	v_add_f32_e32 v106, v106, v74
	v_add_f32_e32 v130, 1.0, v130
	v_exp_f32_e32 v125, v125
	v_exp_f32_e32 v114, v114
	v_mul_f32_e32 v115, 0xbfb8aa3b, v115
	v_mul_f32_e32 v106, 0xbfb8aa3b, v106
	v_add_f32_e32 v107, v107, v75
	v_rcp_f32_e32 v130, v130
	v_add_f32_e32 v131, 1.0, v131
	v_add_f32_e32 v122, 1.0, v122
	v_exp_f32_e32 v115, v115
	v_exp_f32_e32 v106, v106
	v_mul_f32_e32 v107, 0xbfb8aa3b, v107
	v_add_f32_e32 v108, v108, v76
	v_rcp_f32_e32 v131, v131
	v_rcp_f32_e32 v122, v122
	v_add_f32_e32 v123, 1.0, v123
	v_exp_f32_e32 v107, v107
	v_mul_f32_e32 v108, 0xbfb8aa3b, v108
	v_add_f32_e32 v109, v109, v77
	v_add_f32_e32 v98, v98, v58
	v_rcp_f32_e32 v123, v123
	v_add_f32_e32 v124, 1.0, v124
	v_exp_f32_e32 v108, v108
	v_mul_f32_e32 v109, 0xbfb8aa3b, v109
	v_mul_f32_e32 v98, 0xbfb8aa3b, v98
	v_add_f32_e32 v99, v99, v59
	v_add_f32_e32 v90, v90, v74
	v_rcp_f32_e32 v124, v124
	v_add_f32_e32 v125, 1.0, v125
	v_add_f32_e32 v114, 1.0, v114
	v_exp_f32_e32 v109, v109
	v_exp_f32_e32 v98, v98
	v_mul_f32_e32 v99, 0xbfb8aa3b, v99
	v_mul_f32_e32 v90, 0xbfb8aa3b, v90
	v_add_f32_e32 v91, v91, v75
	v_mul_f32_e32 v138, v138, v130
	v_add_f32_e32 v130, v139, v67
	v_rcp_f32_e32 v125, v125
	v_rcp_f32_e32 v114, v114
	v_add_f32_e32 v115, 1.0, v115
	v_add_f32_e32 v106, 1.0, v106
	v_exp_f32_e32 v99, v99
	v_exp_f32_e32 v90, v90
	v_mul_f32_e32 v91, 0xbfb8aa3b, v91
	v_add_f32_e32 v92, v92, v76
	v_mul_f32_e32 v139, v130, v131
	v_add_f32_e32 v131, v132, v60
	v_mul_f32_e32 v122, v126, v122
	v_add_f32_e32 v126, v127, v79
	v_rcp_f32_e32 v115, v115
	v_rcp_f32_e32 v106, v106
	v_add_f32_e32 v107, 1.0, v107
	v_exp_f32_e32 v91, v91
	v_mul_f32_e32 v92, 0xbfb8aa3b, v92
	v_add_f32_e32 v93, v93, v77
	v_add_f32_e32 v82, v82, v58
	v_mul_f32_e32 v131, 0xbfb8aa3b, v131
	v_mul_f32_e32 v123, v126, v123
	v_add_f32_e32 v126, v128, v80
	v_rcp_f32_e32 v107, v107
	v_add_f32_e32 v108, 1.0, v108
	v_exp_f32_e32 v92, v92
	v_mul_f32_e32 v93, 0xbfb8aa3b, v93
	v_mul_f32_e32 v82, 0xbfb8aa3b, v82
	v_add_f32_e32 v83, v83, v59
	v_add_f32_e32 v50, v50, v58
	v_exp_f32_e32 v131, v131
	v_mul_f32_e32 v124, v126, v124
	v_add_f32_e32 v126, v129, v81
	v_add_f32_e32 v118, v118, v66
	v_rcp_f32_e32 v108, v108
	v_add_f32_e32 v109, 1.0, v109
	v_add_f32_e32 v98, 1.0, v98
	v_exp_f32_e32 v93, v93
	v_exp_f32_e32 v82, v82
	v_mul_f32_e32 v83, 0xbfb8aa3b, v83
	v_mul_f32_e32 v50, 0xbfb8aa3b, v50
	v_add_f32_e32 v51, v51, v59
	v_mul_f32_e32 v125, v126, v125
	v_mul_f32_e32 v126, v118, v114
	v_add_f32_e32 v114, v119, v67
	v_add_f32_e32 v110, v110, v78
	v_rcp_f32_e32 v109, v109
	v_rcp_f32_e32 v98, v98
	v_add_f32_e32 v99, 1.0, v99
	v_add_f32_e32 v90, 1.0, v90
	v_exp_f32_e32 v83, v83
	v_exp_f32_e32 v50, v50
	v_mul_f32_e32 v51, 0xbfb8aa3b, v51
	v_add_f32_e32 v34, v34, v58
	v_mul_f32_e32 v127, v114, v115
	v_add_f32_e32 v115, v116, v60
	v_mul_f32_e32 v106, v110, v106
	v_add_f32_e32 v110, v111, v79
	v_rcp_f32_e32 v99, v99
	v_rcp_f32_e32 v90, v90
	v_add_f32_e32 v91, 1.0, v91
	v_exp_f32_e32 v51, v51
	v_mul_f32_e32 v34, 0xbfb8aa3b, v34
	v_add_f32_e32 v35, v35, v59
	v_mul_f32_e32 v115, 0xbfb8aa3b, v115
	v_mul_f32_e32 v107, v110, v107
	v_add_f32_e32 v110, v112, v80
	v_rcp_f32_e32 v91, v91
	v_add_f32_e32 v92, 1.0, v92
	v_exp_f32_e32 v34, v34
	v_mul_f32_e32 v35, 0xbfb8aa3b, v35
	v_add_f32_e32 v18, v18, v58
	v_add_f32_e32 v131, 1.0, v131
	v_exp_f32_e32 v115, v115
	v_mul_f32_e32 v108, v110, v108
	v_add_f32_e32 v110, v113, v81
	v_add_f32_e32 v102, v102, v66
	v_rcp_f32_e32 v92, v92
	v_add_f32_e32 v93, 1.0, v93
	v_add_f32_e32 v82, 1.0, v82
	v_exp_f32_e32 v35, v35
	v_mul_f32_e32 v18, 0xbfb8aa3b, v18
	v_add_f32_e32 v19, v19, v59
	v_rcp_f32_e32 v131, v131
	v_mul_f32_e32 v109, v110, v109
	v_mul_f32_e32 v110, v102, v98
	v_add_f32_e32 v98, v103, v67
	v_add_f32_e32 v94, v94, v78
	v_rcp_f32_e32 v93, v93
	v_rcp_f32_e32 v82, v82
	v_add_f32_e32 v83, 1.0, v83
	v_add_f32_e32 v50, 1.0, v50
	v_exp_f32_e32 v18, v18
	v_mul_f32_e32 v19, 0xbfb8aa3b, v19
	v_add_f32_e32 v2, v2, v58
	v_mul_f32_e32 v111, v98, v99
	v_add_f32_e32 v99, v100, v60
	v_mul_f32_e32 v90, v94, v90
	v_add_f32_e32 v94, v95, v79
	v_rcp_f32_e32 v83, v83
	v_rcp_f32_e32 v50, v50
	v_add_f32_e32 v51, 1.0, v51
	v_exp_f32_e32 v19, v19
	v_mul_f32_e32 v2, 0xbfb8aa3b, v2
	v_add_f32_e32 v3, v3, v59
	v_add_f32_e32 v134, v134, v74
	v_mul_f32_e32 v99, 0xbfb8aa3b, v99
	v_mul_f32_e32 v91, v94, v91
	v_add_f32_e32 v94, v96, v80
	v_rcp_f32_e32 v51, v51
	v_add_f32_e32 v34, 1.0, v34
	v_exp_f32_e32 v2, v2
	v_mul_f32_e32 v3, 0xbfb8aa3b, v3
	v_mul_f32_e32 v134, 0xbfb8aa3b, v134
	v_add_f32_e32 v135, v135, v75
	v_add_f32_e32 v130, v140, v68
	v_add_f32_e32 v115, 1.0, v115
	v_exp_f32_e32 v99, v99
	v_mul_f32_e32 v92, v94, v92
	v_add_f32_e32 v94, v97, v81
	v_add_f32_e32 v86, v86, v66
	v_rcp_f32_e32 v34, v34
	v_add_f32_e32 v35, 1.0, v35
	v_exp_f32_e32 v3, v3
	v_exp_f32_e32 v134, v134
	v_mul_f32_e32 v135, 0xbfb8aa3b, v135
	v_add_f32_e32 v136, v136, v76
	v_mul_f32_e32 v140, v130, v131
	v_add_f32_e32 v131, v133, v61
	v_rcp_f32_e32 v115, v115
	v_mul_f32_e32 v93, v94, v93
	v_mul_f32_e32 v94, v86, v82
	v_add_f32_e32 v82, v87, v67
	v_add_f32_e32 v54, v54, v66
	v_rcp_f32_e32 v35, v35
	v_add_f32_e32 v18, 1.0, v18
	v_exp_f32_e32 v135, v135
	v_mul_f32_e32 v136, 0xbfb8aa3b, v136
	v_add_f32_e32 v137, v137, v77
	v_mul_f32_e32 v131, 0xbfb8aa3b, v131
	v_mul_f32_e32 v95, v82, v83
	v_add_f32_e32 v83, v84, v60
	v_mul_f32_e32 v54, v54, v50
	v_add_f32_e32 v50, v55, v67
	v_rcp_f32_e32 v18, v18
	v_add_f32_e32 v19, 1.0, v19
	v_exp_f32_e32 v136, v136
	v_mul_f32_e32 v137, 0xbfb8aa3b, v137
	v_exp_f32_e32 v131, v131
	v_mul_f32_e32 v83, 0xbfb8aa3b, v83
	v_mul_f32_e32 v55, v50, v51
	v_add_f32_e32 v51, v52, v60
	v_add_f32_e32 v38, v38, v66
	v_rcp_f32_e32 v19, v19
	v_add_f32_e32 v2, 1.0, v2
	v_exp_f32_e32 v137, v137
	v_add_f32_e32 v114, v120, v68
	v_add_f32_e32 v99, 1.0, v99
	v_exp_f32_e32 v83, v83
	v_mul_f32_e32 v51, 0xbfb8aa3b, v51
	v_mul_f32_e32 v38, v38, v34
	v_add_f32_e32 v34, v39, v67
	v_rcp_f32_e32 v2, v2
	v_add_f32_e32 v3, 1.0, v3
	v_add_f32_e32 v134, 1.0, v134
	v_mul_f32_e32 v120, v114, v115
	v_add_f32_e32 v115, v117, v61
	v_rcp_f32_e32 v99, v99
	v_exp_f32_e32 v51, v51
	v_mul_f32_e32 v39, v34, v35
	v_add_f32_e32 v35, v36, v60
	v_add_f32_e32 v22, v22, v66
	v_rcp_f32_e32 v3, v3
	v_rcp_f32_e32 v134, v134
	v_add_f32_e32 v135, 1.0, v135
	v_mul_f32_e32 v115, 0xbfb8aa3b, v115
	v_mul_f32_e32 v35, 0xbfb8aa3b, v35
	v_mul_f32_e32 v22, v22, v18
	v_add_f32_e32 v18, v23, v67
	v_rcp_f32_e32 v135, v135
	v_add_f32_e32 v136, 1.0, v136
	v_add_f32_e32 v131, 1.0, v131
	v_exp_f32_e32 v115, v115
	v_exp_f32_e32 v35, v35
	v_mul_f32_e32 v23, v18, v19
	v_add_f32_e32 v19, v20, v60
	v_add_f32_e32 v6, v6, v66
	v_rcp_f32_e32 v136, v136
	v_add_f32_e32 v137, 1.0, v137
	v_rcp_f32_e32 v131, v131
	v_add_f32_e32 v98, v104, v68
	v_add_f32_e32 v83, 1.0, v83
	v_mul_f32_e32 v19, 0xbfb8aa3b, v19
	v_mul_f32_e32 v6, v6, v2
	v_add_f32_e32 v2, v7, v67
	v_add_f32_e32 v142, v142, v78
	v_rcp_f32_e32 v137, v137
	v_mul_f32_e32 v104, v98, v99
	v_add_f32_e32 v99, v101, v61
	v_rcp_f32_e32 v83, v83
	v_add_f32_e32 v51, 1.0, v51
	v_exp_f32_e32 v19, v19
	v_mul_f32_e32 v7, v2, v3
	v_add_f32_e32 v3, v4, v60
	v_mul_f32_e32 v134, v142, v134
	v_add_f32_e32 v142, v143, v79
	v_mul_f32_e32 v99, 0xbfb8aa3b, v99
	v_rcp_f32_e32 v51, v51
	v_mul_f32_e32 v3, 0xbfb8aa3b, v3
	v_mul_f32_e32 v135, v142, v135
	v_add_f32_e32 v142, v144, v80
	v_add_f32_e32 v130, v141, v69
	v_add_f32_e32 v115, 1.0, v115
	v_exp_f32_e32 v99, v99
	v_add_f32_e32 v62, v62, v74
	v_add_f32_e32 v35, 1.0, v35
	v_exp_f32_e32 v3, v3
	v_mul_f32_e32 v136, v142, v136
	v_add_f32_e32 v142, v145, v81
	v_mul_f32_e32 v141, v130, v131
	v_lshl_add_u64 v[130:131], v[172:173], 0, v[182:183]
	v_cvt_pk_bf16_f32 v132, v134, v135
	v_rcp_f32_e32 v115, v115
	v_add_f32_e32 v82, v88, v68
	v_mul_f32_e32 v62, 0xbfb8aa3b, v62
	v_add_f32_e32 v63, v63, v75
	v_rcp_f32_e32 v35, v35
	v_mul_f32_e32 v137, v142, v137
	v_cvt_pk_bf16_f32 v133, v136, v137
	v_cvt_pk_bf16_f32 v134, v138, v139
	v_cvt_pk_bf16_f32 v135, v140, v141
	global_store_dwordx4 v[130:131], v[132:135], off
	v_mul_f32_e32 v88, v82, v83
	v_add_f32_e32 v83, v85, v61
	v_or_b32_e32 v132, 16, v174
	v_exp_f32_e32 v62, v62
	v_mul_f32_e32 v63, 0xbfb8aa3b, v63
	v_add_f32_e32 v64, v64, v76
	v_add_f32_e32 v50, v56, v68
	v_add_f32_e32 v42, v42, v74
	v_add_f32_e32 v19, 1.0, v19
	v_ashrrev_i32_e32 v133, 31, v132
	v_mul_f32_e32 v83, 0xbfb8aa3b, v83
	v_exp_f32_e32 v63, v63
	v_mul_f32_e32 v64, 0xbfb8aa3b, v64
	v_add_f32_e32 v65, v65, v77
	v_mul_f32_e32 v56, v50, v51
	v_add_f32_e32 v51, v53, v61
	v_mul_f32_e32 v42, 0xbfb8aa3b, v42
	v_add_f32_e32 v43, v43, v75
	v_rcp_f32_e32 v19, v19
	v_lshlrev_b64 v[132:133], 11, v[132:133]
	v_add_f32_e32 v114, v121, v69
	v_add_f32_e32 v99, 1.0, v99
	v_exp_f32_e32 v83, v83
	v_exp_f32_e32 v64, v64
	v_mul_f32_e32 v65, 0xbfb8aa3b, v65
	v_mul_f32_e32 v51, 0xbfb8aa3b, v51
	v_exp_f32_e32 v42, v42
	v_mul_f32_e32 v43, 0xbfb8aa3b, v43
	v_add_f32_e32 v44, v44, v76
	v_add_f32_e32 v34, v40, v68
	v_add_f32_e32 v26, v26, v74
	v_add_f32_e32 v3, 1.0, v3
	v_mul_f32_e32 v117, v114, v115
	v_lshl_add_u64 v[118:119], v[172:173], 0, v[132:133]
	v_cvt_pk_bf16_f32 v114, v122, v123
	v_rcp_f32_e32 v99, v99
	v_exp_f32_e32 v65, v65
	v_exp_f32_e32 v51, v51
	v_exp_f32_e32 v43, v43
	v_mul_f32_e32 v44, 0xbfb8aa3b, v44
	v_add_f32_e32 v45, v45, v77
	v_mul_f32_e32 v40, v34, v35
	v_add_f32_e32 v35, v37, v61
	v_mul_f32_e32 v26, 0xbfb8aa3b, v26
	v_add_f32_e32 v27, v27, v75
	v_rcp_f32_e32 v3, v3
	v_cvt_pk_bf16_f32 v115, v124, v125
	v_cvt_pk_bf16_f32 v116, v126, v127
	v_cvt_pk_bf16_f32 v117, v120, v117
	global_store_dwordx4 v[118:119], v[114:117], off
	v_add_f32_e32 v62, 1.0, v62
	v_exp_f32_e32 v44, v44
	v_or_b32_e32 v114, 32, v174
	v_mul_f32_e32 v45, 0xbfb8aa3b, v45
	v_mul_f32_e32 v35, 0xbfb8aa3b, v35
	v_exp_f32_e32 v26, v26
	v_mul_f32_e32 v27, 0xbfb8aa3b, v27
	v_add_f32_e32 v28, v28, v76
	v_add_f32_e32 v18, v24, v68
	v_add_f32_e32 v10, v10, v74
	v_ashrrev_i32_e32 v115, 31, v114
	v_rcp_f32_e32 v62, v62
	v_add_f32_e32 v63, 1.0, v63
	v_exp_f32_e32 v45, v45
	v_exp_f32_e32 v35, v35
	v_exp_f32_e32 v27, v27
	v_mul_f32_e32 v28, 0xbfb8aa3b, v28
	v_add_f32_e32 v29, v29, v77
	v_mul_f32_e32 v24, v18, v19
	v_add_f32_e32 v19, v21, v61
	v_mul_f32_e32 v10, 0xbfb8aa3b, v10
	v_add_f32_e32 v11, v11, v75
	v_lshlrev_b64 v[114:115], 11, v[114:115]
	v_add_f32_e32 v98, v105, v69
	v_add_f32_e32 v83, 1.0, v83
	v_rcp_f32_e32 v63, v63
	v_add_f32_e32 v64, 1.0, v64
	v_add_f32_e32 v42, 1.0, v42
	v_exp_f32_e32 v28, v28
	v_mul_f32_e32 v29, 0xbfb8aa3b, v29
	v_mul_f32_e32 v19, 0xbfb8aa3b, v19
	v_exp_f32_e32 v10, v10
	v_mul_f32_e32 v11, 0xbfb8aa3b, v11
	v_add_f32_e32 v12, v12, v76
	v_add_f32_e32 v2, v8, v68
	v_mul_f32_e32 v101, v98, v99
	v_lshl_add_u64 v[102:103], v[172:173], 0, v[114:115]
	v_cvt_pk_bf16_f32 v98, v106, v107
	v_rcp_f32_e32 v83, v83
	v_rcp_f32_e32 v64, v64
	v_add_f32_e32 v65, 1.0, v65
	v_add_f32_e32 v51, 1.0, v51
	v_rcp_f32_e32 v42, v42
	v_add_f32_e32 v43, 1.0, v43
	v_exp_f32_e32 v29, v29
	v_exp_f32_e32 v19, v19
	v_exp_f32_e32 v11, v11
	v_mul_f32_e32 v12, 0xbfb8aa3b, v12
	v_add_f32_e32 v13, v13, v77
	v_mul_f32_e32 v8, v2, v3
	v_add_f32_e32 v3, v5, v61
	v_cvt_pk_bf16_f32 v99, v108, v109
	v_cvt_pk_bf16_f32 v100, v110, v111
	v_cvt_pk_bf16_f32 v101, v104, v101
	global_store_dwordx4 v[102:103], v[98:101], off
	v_add_f32_e32 v70, v70, v78
	v_rcp_f32_e32 v65, v65
	v_or_b32_e32 v98, 48, v174
	v_rcp_f32_e32 v51, v51
	v_rcp_f32_e32 v43, v43
	v_add_f32_e32 v44, 1.0, v44
	v_add_f32_e32 v26, 1.0, v26
	v_exp_f32_e32 v12, v12
	v_mul_f32_e32 v13, 0xbfb8aa3b, v13
	v_mul_f32_e32 v3, 0xbfb8aa3b, v3
	v_ashrrev_i32_e32 v99, 31, v98
	v_mul_f32_e32 v62, v70, v62
	v_add_f32_e32 v70, v71, v79
	v_rcp_f32_e32 v44, v44
	v_add_f32_e32 v45, 1.0, v45
	v_add_f32_e32 v35, 1.0, v35
	v_rcp_f32_e32 v26, v26
	v_add_f32_e32 v27, 1.0, v27
	v_exp_f32_e32 v13, v13
	v_exp_f32_e32 v3, v3
	v_lshlrev_b64 v[98:99], 11, v[98:99]
	v_add_f32_e32 v82, v89, v69
	v_mul_f32_e32 v63, v70, v63
	v_add_f32_e32 v70, v72, v80
	v_add_f32_e32 v46, v46, v78
	v_rcp_f32_e32 v45, v45
	v_rcp_f32_e32 v35, v35
	v_rcp_f32_e32 v27, v27
	v_add_f32_e32 v28, 1.0, v28
	v_add_f32_e32 v10, 1.0, v10
	v_mul_f32_e32 v85, v82, v83
	v_lshl_add_u64 v[86:87], v[172:173], 0, v[98:99]
	v_mul_f32_e32 v64, v70, v64
	v_add_f32_e32 v70, v73, v81
	v_add_f32_e32 v50, v57, v69
	v_mul_f32_e32 v42, v46, v42
	v_add_f32_e32 v46, v47, v79
	v_rcp_f32_e32 v28, v28
	v_add_f32_e32 v29, 1.0, v29
	v_add_f32_e32 v19, 1.0, v19
	v_rcp_f32_e32 v10, v10
	v_add_f32_e32 v11, 1.0, v11
	v_cvt_pk_bf16_f32 v82, v90, v91
	v_cvt_pk_bf16_f32 v83, v92, v93
	v_cvt_pk_bf16_f32 v84, v94, v95
	v_cvt_pk_bf16_f32 v85, v88, v85
	global_store_dwordx4 v[86:87], v[82:85], off
	v_mul_f32_e32 v65, v70, v65
	v_mul_f32_e32 v53, v50, v51
	v_cvt_pk_bf16_f32 v50, v62, v63
	v_cvt_pk_bf16_f32 v51, v64, v65
	v_cvt_pk_bf16_f32 v52, v54, v55
	v_add_co_u32_e32 v54, vcc, s67, v130
	v_mul_f32_e32 v43, v46, v43
	v_add_f32_e32 v46, v48, v80
	v_add_f32_e32 v30, v30, v78
	v_rcp_f32_e32 v29, v29
	v_rcp_f32_e32 v19, v19
	v_rcp_f32_e32 v11, v11
	v_add_f32_e32 v12, 1.0, v12
	v_addc_co_u32_e32 v55, vcc, 0, v131, vcc
	v_mul_f32_e32 v44, v46, v44
	v_add_f32_e32 v46, v49, v81
	v_add_f32_e32 v34, v41, v69
	v_mul_f32_e32 v26, v30, v26
	v_add_f32_e32 v30, v31, v79
	v_rcp_f32_e32 v12, v12
	v_add_f32_e32 v13, 1.0, v13
	v_add_f32_e32 v3, 1.0, v3
	v_cvt_pk_bf16_f32 v53, v56, v53
	global_store_dwordx4 v[54:55], v[50:53], off
	v_mul_f32_e32 v45, v46, v45
	v_mul_f32_e32 v37, v34, v35
	v_cvt_pk_bf16_f32 v34, v42, v43
	v_cvt_pk_bf16_f32 v35, v44, v45
	v_cvt_pk_bf16_f32 v36, v38, v39
	v_add_co_u32_e32 v38, vcc, s68, v130
	v_mul_f32_e32 v27, v30, v27
	v_add_f32_e32 v30, v32, v80
	v_add_f32_e32 v14, v14, v78
	v_rcp_f32_e32 v13, v13
	v_rcp_f32_e32 v3, v3
	v_addc_co_u32_e32 v39, vcc, 0, v131, vcc
	v_mul_f32_e32 v28, v30, v28
	v_add_f32_e32 v30, v33, v81
	v_add_f32_e32 v18, v25, v69
	v_mul_f32_e32 v10, v14, v10
	v_add_f32_e32 v14, v15, v79
	v_cvt_pk_bf16_f32 v37, v40, v37
	global_store_dwordx4 v[38:39], v[34:37], off
	v_mul_f32_e32 v29, v30, v29
	v_mul_f32_e32 v21, v18, v19
	v_cvt_pk_bf16_f32 v18, v26, v27
	v_cvt_pk_bf16_f32 v19, v28, v29
	v_cvt_pk_bf16_f32 v20, v22, v23
	v_add_co_u32_e32 v22, vcc, s2, v130
	v_mul_f32_e32 v11, v14, v11
	v_add_f32_e32 v14, v16, v80
	v_addc_co_u32_e32 v23, vcc, 0, v131, vcc
	v_mul_f32_e32 v12, v14, v12
	v_add_f32_e32 v14, v17, v81
	v_add_f32_e32 v2, v9, v69
	v_cvt_pk_bf16_f32 v21, v24, v21
	global_store_dwordx4 v[22:23], v[18:21], off
	v_mul_f32_e32 v13, v14, v13
	v_mul_f32_e32 v5, v2, v3
	v_cvt_pk_bf16_f32 v2, v10, v11
	v_cvt_pk_bf16_f32 v3, v12, v13
	v_cvt_pk_bf16_f32 v4, v6, v7
	v_add_co_u32_e32 v6, vcc, 0x58000, v130
	s_mov_b32 s2, s48
	s_nop 0
	v_addc_co_u32_e32 v7, vcc, 0, v131, vcc
	s_and_b64 vcc, exec, s[38:39]
	v_cvt_pk_bf16_f32 v5, v8, v5
	global_store_dwordx4 v[6:7], v[2:5], off
	s_cbranch_vccz .LBB0_88
	s_waitcnt vmcnt(8)
	s_cmpk_gt_u32 s35, 0xff
	s_cbranch_scc1 .LBB0_99
	s_barrier

.Lkprio_3:
.LBB0_260:
	s_add_u32 s22, s0, 0xfffc0080
	s_addc_u32 s23, s1, -1
	s_add_i32 s60, 0, 0x10000
	v_add_u32_e32 v142, s60, v178
	ds_read_b128 v[130:133], v142
	ds_read_b128 v[134:137], v142 offset:1024
	ds_read_b128 v[138:141], v142 offset:2048
	ds_read_b128 v[142:145], v142 offset:3072
	s_cmp_eq_u32 s59, 12
	s_cselect_b32 s47, s35, s23
	s_cselect_b32 s46, s55, s22
	s_cselect_b32 s23, s31, s58
	s_cselect_b32 s22, s56, s57
	v_lshl_add_u64 v[186:187], s[0:1], 0, v[168:169]
	s_add_i32 m0, s27, 0xc000
	ds_read_b128 v[172:175], v180
	ds_read_b128 v[182:185], v180 offset:1024
	ds_read_b128 v[206:209], v180 offset:2048
	ds_read_b128 v[210:213], v180 offset:3072
	ds_read_b128 v[214:217], v180 offset:4096
	ds_read_b128 v[218:221], v180 offset:5120
	ds_read_b128 v[222:225], v180 offset:6144
	ds_read_b128 v[226:229], v180 offset:7168
	global_load_lds_dwordx4 v[186:187], off
	s_add_i32 m0, s27, 0xe000
	v_lshl_add_u64 v[186:187], s[0:1], 0, v[170:171]
	global_load_lds_dwordx4 v[186:187], off
	s_waitcnt lgkmcnt(8)
	s_barrier
	s_waitcnt lgkmcnt(7)
	v_mfma_f32_16x16x32_bf16 v[126:129], v[130:133], v[172:175], v[126:129]
	v_mfma_f32_16x16x32_bf16 v[122:125], v[138:141], v[172:175], v[122:125]
	s_waitcnt lgkmcnt(5)
	v_mfma_f32_16x16x32_bf16 v[110:113], v[130:133], v[206:209], v[110:113]
	v_mfma_f32_16x16x32_bf16 v[106:109], v[138:141], v[206:209], v[106:109]
	s_waitcnt lgkmcnt(3)
	v_mfma_f32_16x16x32_bf16 v[94:97], v[130:133], v[214:217], v[94:97]
	v_mfma_f32_16x16x32_bf16 v[90:93], v[138:141], v[214:217], v[90:93]
	s_waitcnt lgkmcnt(1)
	v_mfma_f32_16x16x32_bf16 v[78:81], v[130:133], v[222:225], v[78:81]
	v_mfma_f32_16x16x32_bf16 v[74:77], v[138:141], v[222:225], v[74:77]
	v_mfma_f32_16x16x32_bf16 v[126:129], v[134:137], v[182:185], v[126:129]
	v_mfma_f32_16x16x32_bf16 v[122:125], v[142:145], v[182:185], v[122:125]
	v_mfma_f32_16x16x32_bf16 v[110:113], v[134:137], v[210:213], v[110:113]
	v_mfma_f32_16x16x32_bf16 v[106:109], v[142:145], v[210:213], v[106:109]
	v_mfma_f32_16x16x32_bf16 v[94:97], v[134:137], v[218:221], v[94:97]
	v_mfma_f32_16x16x32_bf16 v[90:93], v[142:145], v[218:221], v[90:93]
	s_waitcnt lgkmcnt(0)
	v_mfma_f32_16x16x32_bf16 v[78:81], v[134:137], v[226:229], v[78:81]
	v_mfma_f32_16x16x32_bf16 v[74:77], v[142:145], v[226:229], v[74:77]
	s_barrier
	s_add_i32 s62, 0, 0x14000
	s_add_i32 s60, s60, s25
	v_add_u32_e32 v181, s62, v178
	v_lshl_add_u64 v[186:187], s[22:23], 0, v[0:1]
	s_mov_b32 m0, s60
	ds_read_b128 v[230:233], v181
	ds_read_b128 v[234:237], v181 offset:1024
	ds_read_b128 v[238:241], v181 offset:2048
	ds_read_b128 v[242:245], v181 offset:3072
	global_load_lds_dwordx4 v[186:187], off
	s_add_i32 m0, s60, 0x2000
	v_lshl_add_u64 v[246:247], s[22:23], 0, v[162:163]
	global_load_lds_dwordx4 v[246:247], off
	s_barrier
	s_waitcnt lgkmcnt(3)
	v_mfma_f32_16x16x32_bf16 v[118:121], v[230:233], v[172:175], v[118:121]
	s_waitcnt lgkmcnt(1)
	v_mfma_f32_16x16x32_bf16 v[114:117], v[238:241], v[172:175], v[114:117]
	v_mfma_f32_16x16x32_bf16 v[102:105], v[230:233], v[206:209], v[102:105]
	v_mfma_f32_16x16x32_bf16 v[98:101], v[238:241], v[206:209], v[98:101]
	v_mfma_f32_16x16x32_bf16 v[86:89], v[230:233], v[214:217], v[86:89]
	v_mfma_f32_16x16x32_bf16 v[82:85], v[238:241], v[214:217], v[82:85]
	v_mfma_f32_16x16x32_bf16 v[70:73], v[230:233], v[222:225], v[70:73]
	v_mfma_f32_16x16x32_bf16 v[66:69], v[238:241], v[222:225], v[66:69]
	v_mfma_f32_16x16x32_bf16 v[118:121], v[234:237], v[182:185], v[118:121]
	s_waitcnt lgkmcnt(0)
	v_mfma_f32_16x16x32_bf16 v[114:117], v[242:245], v[182:185], v[114:117]
	v_mfma_f32_16x16x32_bf16 v[102:105], v[234:237], v[210:213], v[102:105]
	v_mfma_f32_16x16x32_bf16 v[98:101], v[242:245], v[210:213], v[98:101]
	v_mfma_f32_16x16x32_bf16 v[86:89], v[234:237], v[218:221], v[86:89]
	v_mfma_f32_16x16x32_bf16 v[82:85], v[242:245], v[218:221], v[82:85]
	v_mfma_f32_16x16x32_bf16 v[70:73], v[234:237], v[226:229], v[70:73]
	v_mfma_f32_16x16x32_bf16 v[66:69], v[242:245], v[226:229], v[66:69]
	s_barrier
	s_mov_b32 m0, s27
	v_lshl_add_u64 v[248:249], s[46:47], 0, v[166:167]
	ds_read_b128 v[172:175], v180 offset:16384
	ds_read_b128 v[182:185], v180 offset:17408
	ds_read_b128 v[206:209], v180 offset:18432
	ds_read_b128 v[210:213], v180 offset:19456
	ds_read_b128 v[214:217], v180 offset:20480
	ds_read_b128 v[218:221], v180 offset:21504
	ds_read_b128 v[222:225], v180 offset:22528
	ds_read_b128 v[226:229], v180 offset:23552
	global_load_lds_dwordx4 v[248:249], off
	s_mov_b32 m0, s45
	v_lshl_add_u64 v[250:251], s[46:47], 0, v[164:165]
	global_load_lds_dwordx4 v[250:251], off
	s_barrier
	s_waitcnt lgkmcnt(7)
	v_mfma_f32_16x16x32_bf16 v[62:65], v[130:133], v[172:175], v[62:65]
	v_mfma_f32_16x16x32_bf16 v[58:61], v[138:141], v[172:175], v[58:61]
	s_waitcnt lgkmcnt(5)
	v_mfma_f32_16x16x32_bf16 v[50:53], v[130:133], v[206:209], v[50:53]
	v_mfma_f32_16x16x32_bf16 v[42:45], v[138:141], v[206:209], v[42:45]
	s_waitcnt lgkmcnt(3)
	v_mfma_f32_16x16x32_bf16 v[34:37], v[130:133], v[214:217], v[34:37]
	v_mfma_f32_16x16x32_bf16 v[26:29], v[138:141], v[214:217], v[26:29]
	s_waitcnt lgkmcnt(1)
	v_mfma_f32_16x16x32_bf16 v[18:21], v[130:133], v[222:225], v[18:21]
	v_mfma_f32_16x16x32_bf16 v[10:13], v[138:141], v[222:225], v[10:13]
	v_mfma_f32_16x16x32_bf16 v[62:65], v[134:137], v[182:185], v[62:65]
	v_mfma_f32_16x16x32_bf16 v[58:61], v[142:145], v[182:185], v[58:61]
	v_mfma_f32_16x16x32_bf16 v[50:53], v[134:137], v[210:213], v[50:53]
	v_mfma_f32_16x16x32_bf16 v[42:45], v[142:145], v[210:213], v[42:45]
	v_mfma_f32_16x16x32_bf16 v[34:37], v[134:137], v[218:221], v[34:37]
	v_mfma_f32_16x16x32_bf16 v[26:29], v[142:145], v[218:221], v[26:29]
	s_waitcnt lgkmcnt(0)
	v_mfma_f32_16x16x32_bf16 v[18:21], v[134:137], v[226:229], v[18:21]
	v_mfma_f32_16x16x32_bf16 v[10:13], v[142:145], v[226:229], v[10:13]
	s_barrier
	s_add_u32 s60, s22, 0x40000
	s_addc_u32 s61, s23, 0
	s_add_i32 s62, s62, s25
	s_mov_b32 m0, s62
	v_lshl_add_u64 v[130:131], s[60:61], 0, v[0:1]
	global_load_lds_dwordx4 v[130:131], off
	s_add_i32 m0, s62, 0x2000
	v_lshl_add_u64 v[130:131], s[60:61], 0, v[162:163]
	global_load_lds_dwordx4 v[130:131], off
	s_waitcnt vmcnt(6)
	s_barrier
	v_mfma_f32_16x16x32_bf16 v[54:57], v[230:233], v[172:175], v[54:57]
	v_mfma_f32_16x16x32_bf16 v[46:49], v[238:241], v[172:175], v[46:49]
	v_mfma_f32_16x16x32_bf16 v[38:41], v[230:233], v[206:209], v[38:41]
	v_mfma_f32_16x16x32_bf16 v[30:33], v[238:241], v[206:209], v[30:33]
	v_mfma_f32_16x16x32_bf16 v[22:25], v[230:233], v[214:217], v[22:25]
	v_mfma_f32_16x16x32_bf16 v[14:17], v[238:241], v[214:217], v[14:17]
	v_mfma_f32_16x16x32_bf16 v[6:9], v[230:233], v[222:225], v[6:9]
	v_mfma_f32_16x16x32_bf16 v[2:5], v[238:241], v[222:225], v[2:5]
	v_mfma_f32_16x16x32_bf16 v[54:57], v[234:237], v[182:185], v[54:57]
	v_mfma_f32_16x16x32_bf16 v[46:49], v[242:245], v[182:185], v[46:49]
	v_mfma_f32_16x16x32_bf16 v[38:41], v[234:237], v[210:213], v[38:41]
	v_mfma_f32_16x16x32_bf16 v[30:33], v[242:245], v[210:213], v[30:33]
	v_mfma_f32_16x16x32_bf16 v[22:25], v[234:237], v[218:221], v[22:25]
	v_mfma_f32_16x16x32_bf16 v[14:17], v[242:245], v[218:221], v[14:17]
	v_mfma_f32_16x16x32_bf16 v[6:9], v[234:237], v[226:229], v[6:9]
	v_mfma_f32_16x16x32_bf16 v[2:5], v[242:245], v[226:229], v[2:5]
	s_barrier
	s_add_i32 s60, 0, 0x18000
	v_add_u32_e32 v142, s60, v178
	ds_read_b128 v[130:133], v142
	ds_read_b128 v[134:137], v142 offset:1024
	ds_read_b128 v[138:141], v142 offset:2048
	ds_read_b128 v[142:145], v142 offset:3072
	s_add_u32 s46, s46, 0x40000
	s_addc_u32 s47, s47, 0
	s_mov_b32 m0, s48
	v_lshl_add_u64 v[230:231], s[46:47], 0, v[166:167]
	ds_read_b128 v[172:175], v180 offset:32768
	ds_read_b128 v[182:185], v180 offset:33792
	ds_read_b128 v[206:209], v180 offset:34816
	ds_read_b128 v[210:213], v180 offset:35840
	ds_read_b128 v[214:217], v180 offset:36864
	ds_read_b128 v[218:221], v180 offset:37888
	ds_read_b128 v[222:225], v180 offset:38912
	ds_read_b128 v[226:229], v180 offset:39936
	global_load_lds_dwordx4 v[230:231], off
	s_mov_b32 m0, s49
	v_lshl_add_u64 v[230:231], s[46:47], 0, v[164:165]
	global_load_lds_dwordx4 v[230:231], off
	s_waitcnt lgkmcnt(8)
	s_barrier
	s_waitcnt lgkmcnt(7)
	v_mfma_f32_16x16x32_bf16 v[126:129], v[130:133], v[172:175], v[126:129]
	v_mfma_f32_16x16x32_bf16 v[122:125], v[138:141], v[172:175], v[122:125]
	s_waitcnt lgkmcnt(5)
	v_mfma_f32_16x16x32_bf16 v[110:113], v[130:133], v[206:209], v[110:113]
	v_mfma_f32_16x16x32_bf16 v[106:109], v[138:141], v[206:209], v[106:109]
	s_waitcnt lgkmcnt(3)
	v_mfma_f32_16x16x32_bf16 v[94:97], v[130:133], v[214:217], v[94:97]
	v_mfma_f32_16x16x32_bf16 v[90:93], v[138:141], v[214:217], v[90:93]
	s_waitcnt lgkmcnt(1)
	v_mfma_f32_16x16x32_bf16 v[78:81], v[130:133], v[222:225], v[78:81]
	v_mfma_f32_16x16x32_bf16 v[74:77], v[138:141], v[222:225], v[74:77]
	v_mfma_f32_16x16x32_bf16 v[126:129], v[134:137], v[182:185], v[126:129]
	v_mfma_f32_16x16x32_bf16 v[122:125], v[142:145], v[182:185], v[122:125]
	v_mfma_f32_16x16x32_bf16 v[110:113], v[134:137], v[210:213], v[110:113]
	v_mfma_f32_16x16x32_bf16 v[106:109], v[142:145], v[210:213], v[106:109]
	v_mfma_f32_16x16x32_bf16 v[94:97], v[134:137], v[218:221], v[94:97]
	v_mfma_f32_16x16x32_bf16 v[90:93], v[142:145], v[218:221], v[90:93]
	s_waitcnt lgkmcnt(0)
	v_mfma_f32_16x16x32_bf16 v[78:81], v[134:137], v[226:229], v[78:81]
	v_mfma_f32_16x16x32_bf16 v[74:77], v[142:145], v[226:229], v[74:77]
	s_barrier
	s_add_i32 s46, 0, 0x1c000
	s_add_i32 s47, s60, s25
	v_add_u32_e32 v181, s46, v178
	v_lshl_add_u64 v[186:187], v[186:187], 0, s[94:95]
	s_mov_b32 m0, s47
	ds_read_b128 v[230:233], v181
	ds_read_b128 v[234:237], v181 offset:1024
	ds_read_b128 v[238:241], v181 offset:2048
	ds_read_b128 v[242:245], v181 offset:3072
	global_load_lds_dwordx4 v[186:187], off
	s_add_i32 m0, s47, 0x2000
	v_lshl_add_u64 v[186:187], v[246:247], 0, s[94:95]
	global_load_lds_dwordx4 v[186:187], off
	s_barrier
	s_waitcnt lgkmcnt(3)
	v_mfma_f32_16x16x32_bf16 v[118:121], v[230:233], v[172:175], v[118:121]
	s_waitcnt lgkmcnt(1)
	v_mfma_f32_16x16x32_bf16 v[114:117], v[238:241], v[172:175], v[114:117]
	v_mfma_f32_16x16x32_bf16 v[102:105], v[230:233], v[206:209], v[102:105]
	v_mfma_f32_16x16x32_bf16 v[98:101], v[238:241], v[206:209], v[98:101]
	v_mfma_f32_16x16x32_bf16 v[86:89], v[230:233], v[214:217], v[86:89]
	v_mfma_f32_16x16x32_bf16 v[82:85], v[238:241], v[214:217], v[82:85]
	v_mfma_f32_16x16x32_bf16 v[70:73], v[230:233], v[222:225], v[70:73]
	v_mfma_f32_16x16x32_bf16 v[66:69], v[238:241], v[222:225], v[66:69]
	v_mfma_f32_16x16x32_bf16 v[118:121], v[234:237], v[182:185], v[118:121]
	s_waitcnt lgkmcnt(0)
	v_mfma_f32_16x16x32_bf16 v[114:117], v[242:245], v[182:185], v[114:117]
	v_mfma_f32_16x16x32_bf16 v[102:105], v[234:237], v[210:213], v[102:105]
	v_mfma_f32_16x16x32_bf16 v[98:101], v[242:245], v[210:213], v[98:101]
	v_mfma_f32_16x16x32_bf16 v[86:89], v[234:237], v[218:221], v[86:89]
	v_mfma_f32_16x16x32_bf16 v[82:85], v[242:245], v[218:221], v[82:85]
	v_mfma_f32_16x16x32_bf16 v[70:73], v[234:237], v[226:229], v[70:73]
	v_mfma_f32_16x16x32_bf16 v[66:69], v[242:245], v[226:229], v[66:69]
	s_barrier
	s_mov_b32 m0, s51
	v_lshl_add_u64 v[186:187], v[248:249], 0, s[94:95]
	ds_read_b128 v[172:175], v180 offset:49152
	ds_read_b128 v[182:185], v180 offset:50176
	ds_read_b128 v[206:209], v180 offset:51200
	ds_read_b128 v[210:213], v180 offset:52224
	ds_read_b128 v[214:217], v180 offset:53248
	ds_read_b128 v[218:221], v180 offset:54272
	ds_read_b128 v[222:225], v180 offset:55296
	ds_read_b128 v[226:229], v180 offset:56320
	global_load_lds_dwordx4 v[186:187], off
	s_mov_b32 m0, s52
	v_lshl_add_u64 v[186:187], v[250:251], 0, s[94:95]
	global_load_lds_dwordx4 v[186:187], off
	s_barrier
	s_waitcnt lgkmcnt(7)
	v_mfma_f32_16x16x32_bf16 v[62:65], v[130:133], v[172:175], v[62:65]
	v_mfma_f32_16x16x32_bf16 v[58:61], v[138:141], v[172:175], v[58:61]
	s_waitcnt lgkmcnt(5)
	v_mfma_f32_16x16x32_bf16 v[50:53], v[130:133], v[206:209], v[50:53]
	v_mfma_f32_16x16x32_bf16 v[42:45], v[138:141], v[206:209], v[42:45]
	s_waitcnt lgkmcnt(3)
	v_mfma_f32_16x16x32_bf16 v[34:37], v[130:133], v[214:217], v[34:37]
	v_mfma_f32_16x16x32_bf16 v[26:29], v[138:141], v[214:217], v[26:29]
	s_waitcnt lgkmcnt(1)
	v_mfma_f32_16x16x32_bf16 v[18:21], v[130:133], v[222:225], v[18:21]
	v_mfma_f32_16x16x32_bf16 v[10:13], v[138:141], v[222:225], v[10:13]
	v_mfma_f32_16x16x32_bf16 v[62:65], v[134:137], v[182:185], v[62:65]
	v_mfma_f32_16x16x32_bf16 v[58:61], v[142:145], v[182:185], v[58:61]
	v_mfma_f32_16x16x32_bf16 v[50:53], v[134:137], v[210:213], v[50:53]
	v_mfma_f32_16x16x32_bf16 v[42:45], v[142:145], v[210:213], v[42:45]
	v_mfma_f32_16x16x32_bf16 v[34:37], v[134:137], v[218:221], v[34:37]
	v_mfma_f32_16x16x32_bf16 v[26:29], v[142:145], v[218:221], v[26:29]
	s_waitcnt lgkmcnt(0)
	v_mfma_f32_16x16x32_bf16 v[18:21], v[134:137], v[226:229], v[18:21]
	v_mfma_f32_16x16x32_bf16 v[10:13], v[142:145], v[226:229], v[10:13]
	s_barrier
	s_add_u32 s22, s22, 0x40080
	s_addc_u32 s23, s23, 0
	s_add_i32 s46, s46, s25
	s_mov_b32 m0, s46
	v_lshl_add_u64 v[130:131], s[22:23], 0, v[0:1]
	global_load_lds_dwordx4 v[130:131], off
	s_add_i32 m0, s46, 0x2000
	v_lshl_add_u64 v[130:131], s[22:23], 0, v[162:163]
	global_load_lds_dwordx4 v[130:131], off
	s_waitcnt vmcnt(6)
	s_barrier
	v_mfma_f32_16x16x32_bf16 v[54:57], v[230:233], v[172:175], v[54:57]
	v_mfma_f32_16x16x32_bf16 v[46:49], v[238:241], v[172:175], v[46:49]
	v_mfma_f32_16x16x32_bf16 v[38:41], v[230:233], v[206:209], v[38:41]
	v_mfma_f32_16x16x32_bf16 v[30:33], v[238:241], v[206:209], v[30:33]
	v_mfma_f32_16x16x32_bf16 v[22:25], v[230:233], v[214:217], v[22:25]
	v_mfma_f32_16x16x32_bf16 v[14:17], v[238:241], v[214:217], v[14:17]
	v_mfma_f32_16x16x32_bf16 v[6:9], v[230:233], v[222:225], v[6:9]
	v_mfma_f32_16x16x32_bf16 v[2:5], v[238:241], v[222:225], v[2:5]
	v_mfma_f32_16x16x32_bf16 v[54:57], v[234:237], v[182:185], v[54:57]
	v_mfma_f32_16x16x32_bf16 v[46:49], v[242:245], v[182:185], v[46:49]
	v_mfma_f32_16x16x32_bf16 v[38:41], v[234:237], v[210:213], v[38:41]
	v_mfma_f32_16x16x32_bf16 v[30:33], v[242:245], v[210:213], v[30:33]
	v_mfma_f32_16x16x32_bf16 v[22:25], v[234:237], v[218:221], v[22:25]
	v_mfma_f32_16x16x32_bf16 v[14:17], v[242:245], v[218:221], v[14:17]
	v_mfma_f32_16x16x32_bf16 v[6:9], v[234:237], v[226:229], v[6:9]
	v_mfma_f32_16x16x32_bf16 v[2:5], v[242:245], v[226:229], v[2:5]
	s_barrier
	s_add_i32 s59, s59, 2
	s_add_u32 s0, s0, 0x100
	s_addc_u32 s1, s1, 0
	s_add_u32 s57, s57, 0x100
	s_addc_u32 s58, s58, 0
	s_cmp_gt_u32 s59, 13
	s_cbranch_scc0 .LBB0_260
	v_lshl_or_b32 v172, s54, 8, v179
	v_ashrrev_i32_e32 v173, 31, v172
	v_cndmask_b32_e64 v131, 0, 1, s[2:3]
	v_lshl_add_u64 v[174:175], v[172:173], 2, s[8:9]
	v_mov_b32_e32 v130, 0
	v_cmp_ne_u32_e64 s[0:1], 1, v131
	s_andn2_b64 vcc, exec, s[2:3]
	v_mov_b32_e32 v134, 0
	v_mov_b32_e32 v135, 0
	v_mov_b32_e32 v136, 0
	v_mov_b32_e32 v137, 0
	s_cbranch_vccnz .LBB0_263
	global_load_dwordx4 v[134:137], v[174:175], off

.Lkprio_2:
.LBB0_331:
	s_add_u32 s22, s24, 0x100
	s_addc_u32 s23, s25, 0
	s_add_i32 s52, 0, 0x10000
	v_add_u32_e32 v140, s52, v144
	ds_read_b128 v[164:167], v140
	ds_read_b128 v[168:171], v140 offset:1024
	ds_read_b128 v[172:175], v140 offset:2048
	ds_read_b128 v[176:179], v140 offset:3072
	s_cmp_eq_u32 s51, 40
	s_cselect_b32 s29, s3, s23
	s_cselect_b32 s28, s2, s22
	s_cselect_b32 s27, s1, s41
	s_cselect_b32 s26, s0, s40
	v_lshl_add_u64 v[140:141], s[24:25], 0, v[136:137]
	s_add_i32 m0, s35, 0xc000
	ds_read_b128 v[180:183], v162
	ds_read_b128 v[184:187], v162 offset:1024
	ds_read_b128 v[206:209], v162 offset:2048
	ds_read_b128 v[210:213], v162 offset:3072
	ds_read_b128 v[214:217], v162 offset:4096
	ds_read_b128 v[218:221], v162 offset:5120
	ds_read_b128 v[222:225], v162 offset:6144
	ds_read_b128 v[226:229], v162 offset:7168
	global_load_lds_dwordx4 v[140:141], off
	s_add_i32 m0, s35, 0xe000
	v_lshl_add_u64 v[140:141], s[24:25], 0, v[138:139]
	global_load_lds_dwordx4 v[140:141], off
	s_waitcnt lgkmcnt(8)
	s_barrier
	s_waitcnt lgkmcnt(7)
	v_mfma_f32_16x16x32_bf16 v[126:129], v[164:167], v[180:183], v[126:129]
	v_mfma_f32_16x16x32_bf16 v[122:125], v[172:175], v[180:183], v[122:125]
	s_waitcnt lgkmcnt(5)
	v_mfma_f32_16x16x32_bf16 v[114:117], v[164:167], v[206:209], v[114:117]
	v_mfma_f32_16x16x32_bf16 v[106:109], v[172:175], v[206:209], v[106:109]
	s_waitcnt lgkmcnt(3)
	v_mfma_f32_16x16x32_bf16 v[98:101], v[164:167], v[214:217], v[98:101]
	v_mfma_f32_16x16x32_bf16 v[90:93], v[172:175], v[214:217], v[90:93]
	s_waitcnt lgkmcnt(1)
	v_mfma_f32_16x16x32_bf16 v[82:85], v[164:167], v[222:225], v[82:85]
	v_mfma_f32_16x16x32_bf16 v[74:77], v[172:175], v[222:225], v[74:77]
	v_mfma_f32_16x16x32_bf16 v[126:129], v[168:171], v[184:187], v[126:129]
	v_mfma_f32_16x16x32_bf16 v[122:125], v[176:179], v[184:187], v[122:125]
	v_mfma_f32_16x16x32_bf16 v[114:117], v[168:171], v[210:213], v[114:117]
	v_mfma_f32_16x16x32_bf16 v[106:109], v[176:179], v[210:213], v[106:109]
	v_mfma_f32_16x16x32_bf16 v[98:101], v[168:171], v[218:221], v[98:101]
	v_mfma_f32_16x16x32_bf16 v[90:93], v[176:179], v[218:221], v[90:93]
	s_waitcnt lgkmcnt(0)
	v_mfma_f32_16x16x32_bf16 v[82:85], v[168:171], v[226:229], v[82:85]
	v_mfma_f32_16x16x32_bf16 v[74:77], v[176:179], v[226:229], v[74:77]
	s_barrier
	s_add_i32 s53, 0, 0x14000
	v_add_u32_e32 v140, s53, v144
	s_add_i32 s24, s52, s31
	ds_read_b128 v[230:233], v140
	ds_read_b128 v[234:237], v140 offset:1024
	ds_read_b128 v[238:241], v140 offset:2048
	ds_read_b128 v[242:245], v140 offset:3072
	v_lshl_add_u64 v[140:141], s[26:27], 0, v[0:1]
	s_mov_b32 m0, s24
	v_lshl_add_u64 v[246:247], s[26:27], 0, v[130:131]
	global_load_lds_dwordx4 v[140:141], off
	s_add_i32 m0, s24, 0x2000
	s_nop 0
	global_load_lds_dwordx4 v[246:247], off
	s_barrier
	s_waitcnt lgkmcnt(3)
	v_mfma_f32_16x16x32_bf16 v[118:121], v[230:233], v[180:183], v[118:121]
	s_waitcnt lgkmcnt(1)
	v_mfma_f32_16x16x32_bf16 v[110:113], v[238:241], v[180:183], v[110:113]
	v_mfma_f32_16x16x32_bf16 v[102:105], v[230:233], v[206:209], v[102:105]
	v_mfma_f32_16x16x32_bf16 v[94:97], v[238:241], v[206:209], v[94:97]
	v_mfma_f32_16x16x32_bf16 v[86:89], v[230:233], v[214:217], v[86:89]
	v_mfma_f32_16x16x32_bf16 v[78:81], v[238:241], v[214:217], v[78:81]
	v_mfma_f32_16x16x32_bf16 v[70:73], v[230:233], v[222:225], v[70:73]
	v_mfma_f32_16x16x32_bf16 v[66:69], v[238:241], v[222:225], v[66:69]
	v_mfma_f32_16x16x32_bf16 v[118:121], v[234:237], v[184:187], v[118:121]
	s_waitcnt lgkmcnt(0)
	v_mfma_f32_16x16x32_bf16 v[110:113], v[242:245], v[184:187], v[110:113]
	v_mfma_f32_16x16x32_bf16 v[102:105], v[234:237], v[210:213], v[102:105]
	v_mfma_f32_16x16x32_bf16 v[94:97], v[242:245], v[210:213], v[94:97]
	v_mfma_f32_16x16x32_bf16 v[86:89], v[234:237], v[218:221], v[86:89]
	v_mfma_f32_16x16x32_bf16 v[78:81], v[242:245], v[218:221], v[78:81]
	v_mfma_f32_16x16x32_bf16 v[70:73], v[234:237], v[226:229], v[70:73]
	v_mfma_f32_16x16x32_bf16 v[66:69], v[242:245], v[226:229], v[66:69]
	s_barrier
	s_mov_b32 m0, s35
	v_lshl_add_u64 v[248:249], s[28:29], 0, v[134:135]
	ds_read_b128 v[180:183], v162 offset:16384
	ds_read_b128 v[184:187], v162 offset:17408
	ds_read_b128 v[206:209], v162 offset:18432
	ds_read_b128 v[210:213], v162 offset:19456
	ds_read_b128 v[214:217], v162 offset:20480
	ds_read_b128 v[218:221], v162 offset:21504
	ds_read_b128 v[222:225], v162 offset:22528
	ds_read_b128 v[226:229], v162 offset:23552
	global_load_lds_dwordx4 v[248:249], off
	s_mov_b32 m0, s36
	v_lshl_add_u64 v[250:251], s[28:29], 0, v[132:133]
	global_load_lds_dwordx4 v[250:251], off
	s_barrier
	s_waitcnt lgkmcnt(7)
	v_mfma_f32_16x16x32_bf16 v[62:65], v[164:167], v[180:183], v[62:65]
	v_mfma_f32_16x16x32_bf16 v[58:61], v[172:175], v[180:183], v[58:61]
	s_waitcnt lgkmcnt(5)
	v_mfma_f32_16x16x32_bf16 v[50:53], v[164:167], v[206:209], v[50:53]
	v_mfma_f32_16x16x32_bf16 v[42:45], v[172:175], v[206:209], v[42:45]
	s_waitcnt lgkmcnt(3)
	v_mfma_f32_16x16x32_bf16 v[34:37], v[164:167], v[214:217], v[34:37]
	v_mfma_f32_16x16x32_bf16 v[26:29], v[172:175], v[214:217], v[26:29]
	s_waitcnt lgkmcnt(1)
	v_mfma_f32_16x16x32_bf16 v[18:21], v[164:167], v[222:225], v[18:21]
	v_mfma_f32_16x16x32_bf16 v[10:13], v[172:175], v[222:225], v[10:13]
	v_mfma_f32_16x16x32_bf16 v[62:65], v[168:171], v[184:187], v[62:65]
	v_mfma_f32_16x16x32_bf16 v[58:61], v[176:179], v[184:187], v[58:61]
	v_mfma_f32_16x16x32_bf16 v[50:53], v[168:171], v[210:213], v[50:53]
	v_mfma_f32_16x16x32_bf16 v[42:45], v[176:179], v[210:213], v[42:45]
	v_mfma_f32_16x16x32_bf16 v[34:37], v[168:171], v[218:221], v[34:37]
	v_mfma_f32_16x16x32_bf16 v[26:29], v[176:179], v[218:221], v[26:29]
	s_waitcnt lgkmcnt(0)
	v_mfma_f32_16x16x32_bf16 v[18:21], v[168:171], v[226:229], v[18:21]
	v_mfma_f32_16x16x32_bf16 v[10:13], v[176:179], v[226:229], v[10:13]
	s_barrier
	s_add_u32 s24, s26, 0xb0000
	s_addc_u32 s25, s27, 0
	s_add_i32 s52, s53, s31
	s_mov_b32 m0, s52
	v_lshl_add_u64 v[164:165], s[24:25], 0, v[0:1]
	global_load_lds_dwordx4 v[164:165], off
	s_add_i32 m0, s52, 0x2000
	v_lshl_add_u64 v[164:165], s[24:25], 0, v[130:131]
	global_load_lds_dwordx4 v[164:165], off
	s_waitcnt vmcnt(6)
	s_barrier
	v_mfma_f32_16x16x32_bf16 v[54:57], v[230:233], v[180:183], v[54:57]
	v_mfma_f32_16x16x32_bf16 v[46:49], v[238:241], v[180:183], v[46:49]
	v_mfma_f32_16x16x32_bf16 v[38:41], v[230:233], v[206:209], v[38:41]
	v_mfma_f32_16x16x32_bf16 v[30:33], v[238:241], v[206:209], v[30:33]
	v_mfma_f32_16x16x32_bf16 v[22:25], v[230:233], v[214:217], v[22:25]
	v_mfma_f32_16x16x32_bf16 v[14:17], v[238:241], v[214:217], v[14:17]
	v_mfma_f32_16x16x32_bf16 v[6:9], v[230:233], v[222:225], v[6:9]
	v_mfma_f32_16x16x32_bf16 v[2:5], v[238:241], v[222:225], v[2:5]
	v_mfma_f32_16x16x32_bf16 v[54:57], v[234:237], v[184:187], v[54:57]
	v_mfma_f32_16x16x32_bf16 v[46:49], v[242:245], v[184:187], v[46:49]
	v_mfma_f32_16x16x32_bf16 v[38:41], v[234:237], v[210:213], v[38:41]
	v_mfma_f32_16x16x32_bf16 v[30:33], v[242:245], v[210:213], v[30:33]
	v_mfma_f32_16x16x32_bf16 v[22:25], v[234:237], v[218:221], v[22:25]
	v_mfma_f32_16x16x32_bf16 v[14:17], v[242:245], v[218:221], v[14:17]
	v_mfma_f32_16x16x32_bf16 v[6:9], v[234:237], v[226:229], v[6:9]
	v_mfma_f32_16x16x32_bf16 v[2:5], v[242:245], v[226:229], v[2:5]
	s_barrier
	s_add_i32 s52, 0, 0x18000
	v_add_u32_e32 v163, s52, v144
	ds_read_b128 v[164:167], v163
	ds_read_b128 v[168:171], v163 offset:1024
	ds_read_b128 v[172:175], v163 offset:2048
	ds_read_b128 v[176:179], v163 offset:3072
	s_add_u32 s24, s28, 0xb0000
	s_addc_u32 s25, s29, 0
	s_mov_b32 m0, s37
	v_lshl_add_u64 v[230:231], s[24:25], 0, v[134:135]
	ds_read_b128 v[180:183], v162 offset:32768
	ds_read_b128 v[184:187], v162 offset:33792
	ds_read_b128 v[206:209], v162 offset:34816
	ds_read_b128 v[210:213], v162 offset:35840
	ds_read_b128 v[214:217], v162 offset:36864
	ds_read_b128 v[218:221], v162 offset:37888
	ds_read_b128 v[222:225], v162 offset:38912
	ds_read_b128 v[226:229], v162 offset:39936
	global_load_lds_dwordx4 v[230:231], off
	s_mov_b32 m0, s42
	v_lshl_add_u64 v[230:231], s[24:25], 0, v[132:133]
	global_load_lds_dwordx4 v[230:231], off
	s_waitcnt lgkmcnt(8)
	s_barrier
	s_waitcnt lgkmcnt(7)
	v_mfma_f32_16x16x32_bf16 v[126:129], v[164:167], v[180:183], v[126:129]
	v_mfma_f32_16x16x32_bf16 v[122:125], v[172:175], v[180:183], v[122:125]
	s_waitcnt lgkmcnt(5)
	v_mfma_f32_16x16x32_bf16 v[114:117], v[164:167], v[206:209], v[114:117]
	v_mfma_f32_16x16x32_bf16 v[106:109], v[172:175], v[206:209], v[106:109]
	s_waitcnt lgkmcnt(3)
	v_mfma_f32_16x16x32_bf16 v[98:101], v[164:167], v[214:217], v[98:101]
	v_mfma_f32_16x16x32_bf16 v[90:93], v[172:175], v[214:217], v[90:93]
	s_waitcnt lgkmcnt(1)
	v_mfma_f32_16x16x32_bf16 v[82:85], v[164:167], v[222:225], v[82:85]
	v_mfma_f32_16x16x32_bf16 v[74:77], v[172:175], v[222:225], v[74:77]
	v_mfma_f32_16x16x32_bf16 v[126:129], v[168:171], v[184:187], v[126:129]
	v_mfma_f32_16x16x32_bf16 v[122:125], v[176:179], v[184:187], v[122:125]
	v_mfma_f32_16x16x32_bf16 v[114:117], v[168:171], v[210:213], v[114:117]
	v_mfma_f32_16x16x32_bf16 v[106:109], v[176:179], v[210:213], v[106:109]
	v_mfma_f32_16x16x32_bf16 v[98:101], v[168:171], v[218:221], v[98:101]
	v_mfma_f32_16x16x32_bf16 v[90:93], v[176:179], v[218:221], v[90:93]
	s_waitcnt lgkmcnt(0)
	v_mfma_f32_16x16x32_bf16 v[82:85], v[168:171], v[226:229], v[82:85]
	v_mfma_f32_16x16x32_bf16 v[74:77], v[176:179], v[226:229], v[74:77]
	s_barrier
	s_add_i32 s28, 0, 0x1c000
	s_add_i32 s24, s52, s31
	v_add_u32_e32 v163, s28, v144
	v_lshl_add_u64 v[140:141], v[140:141], 0, s[94:95]
	s_mov_b32 m0, s24
	ds_read_b128 v[230:233], v163
	ds_read_b128 v[234:237], v163 offset:1024
	ds_read_b128 v[238:241], v163 offset:2048
	ds_read_b128 v[242:245], v163 offset:3072
	global_load_lds_dwordx4 v[140:141], off
	s_add_i32 m0, s24, 0x2000
	v_lshl_add_u64 v[140:141], v[246:247], 0, s[94:95]
	global_load_lds_dwordx4 v[140:141], off
	s_barrier
	s_waitcnt lgkmcnt(3)
	v_mfma_f32_16x16x32_bf16 v[118:121], v[230:233], v[180:183], v[118:121]
	s_waitcnt lgkmcnt(1)
	v_mfma_f32_16x16x32_bf16 v[110:113], v[238:241], v[180:183], v[110:113]
	v_mfma_f32_16x16x32_bf16 v[102:105], v[230:233], v[206:209], v[102:105]
	v_mfma_f32_16x16x32_bf16 v[94:97], v[238:241], v[206:209], v[94:97]
	v_mfma_f32_16x16x32_bf16 v[86:89], v[230:233], v[214:217], v[86:89]
	v_mfma_f32_16x16x32_bf16 v[78:81], v[238:241], v[214:217], v[78:81]
	v_mfma_f32_16x16x32_bf16 v[70:73], v[230:233], v[222:225], v[70:73]
	v_mfma_f32_16x16x32_bf16 v[66:69], v[238:241], v[222:225], v[66:69]
	v_mfma_f32_16x16x32_bf16 v[118:121], v[234:237], v[184:187], v[118:121]
	s_waitcnt lgkmcnt(0)
	v_mfma_f32_16x16x32_bf16 v[110:113], v[242:245], v[184:187], v[110:113]
	v_mfma_f32_16x16x32_bf16 v[102:105], v[234:237], v[210:213], v[102:105]
	v_mfma_f32_16x16x32_bf16 v[94:97], v[242:245], v[210:213], v[94:97]
	v_mfma_f32_16x16x32_bf16 v[86:89], v[234:237], v[218:221], v[86:89]
	v_mfma_f32_16x16x32_bf16 v[78:81], v[242:245], v[218:221], v[78:81]
	v_mfma_f32_16x16x32_bf16 v[70:73], v[234:237], v[226:229], v[70:73]
	v_mfma_f32_16x16x32_bf16 v[66:69], v[242:245], v[226:229], v[66:69]
	s_barrier
	s_mov_b32 m0, s44
	v_lshl_add_u64 v[140:141], v[248:249], 0, s[94:95]
	ds_read_b128 v[180:183], v162 offset:49152
	ds_read_b128 v[184:187], v162 offset:50176
	ds_read_b128 v[206:209], v162 offset:51200
	ds_read_b128 v[210:213], v162 offset:52224
	ds_read_b128 v[214:217], v162 offset:53248
	ds_read_b128 v[218:221], v162 offset:54272
	ds_read_b128 v[222:225], v162 offset:55296
	ds_read_b128 v[226:229], v162 offset:56320
	global_load_lds_dwordx4 v[140:141], off
	s_mov_b32 m0, s45
	v_lshl_add_u64 v[140:141], v[250:251], 0, s[94:95]
	global_load_lds_dwordx4 v[140:141], off
	s_barrier
	s_waitcnt lgkmcnt(7)
	v_mfma_f32_16x16x32_bf16 v[62:65], v[164:167], v[180:183], v[62:65]
	v_mfma_f32_16x16x32_bf16 v[58:61], v[172:175], v[180:183], v[58:61]
	s_waitcnt lgkmcnt(5)
	v_mfma_f32_16x16x32_bf16 v[50:53], v[164:167], v[206:209], v[50:53]
	v_mfma_f32_16x16x32_bf16 v[42:45], v[172:175], v[206:209], v[42:45]
	s_waitcnt lgkmcnt(3)
	v_mfma_f32_16x16x32_bf16 v[34:37], v[164:167], v[214:217], v[34:37]
	v_mfma_f32_16x16x32_bf16 v[26:29], v[172:175], v[214:217], v[26:29]
	s_waitcnt lgkmcnt(1)
	v_mfma_f32_16x16x32_bf16 v[18:21], v[164:167], v[222:225], v[18:21]
	v_mfma_f32_16x16x32_bf16 v[10:13], v[172:175], v[222:225], v[10:13]
	v_mfma_f32_16x16x32_bf16 v[62:65], v[168:171], v[184:187], v[62:65]
	v_mfma_f32_16x16x32_bf16 v[58:61], v[176:179], v[184:187], v[58:61]
	v_mfma_f32_16x16x32_bf16 v[50:53], v[168:171], v[210:213], v[50:53]
	v_mfma_f32_16x16x32_bf16 v[42:45], v[176:179], v[210:213], v[42:45]
	v_mfma_f32_16x16x32_bf16 v[34:37], v[168:171], v[218:221], v[34:37]
	v_mfma_f32_16x16x32_bf16 v[26:29], v[176:179], v[218:221], v[26:29]
	s_waitcnt lgkmcnt(0)
	v_mfma_f32_16x16x32_bf16 v[18:21], v[168:171], v[226:229], v[18:21]
	v_mfma_f32_16x16x32_bf16 v[10:13], v[176:179], v[226:229], v[10:13]
	s_barrier
	s_add_u32 s24, s26, 0xb0080
	s_addc_u32 s25, s27, 0
	s_add_i32 s26, s28, s31
	s_mov_b32 m0, s26
	v_lshl_add_u64 v[140:141], s[24:25], 0, v[0:1]
	global_load_lds_dwordx4 v[140:141], off
	s_add_i32 m0, s26, 0x2000
	v_lshl_add_u64 v[140:141], s[24:25], 0, v[130:131]
	global_load_lds_dwordx4 v[140:141], off
	s_waitcnt vmcnt(6)
	s_barrier
	v_mfma_f32_16x16x32_bf16 v[54:57], v[230:233], v[180:183], v[54:57]
	v_mfma_f32_16x16x32_bf16 v[46:49], v[238:241], v[180:183], v[46:49]
	v_mfma_f32_16x16x32_bf16 v[38:41], v[230:233], v[206:209], v[38:41]
	v_mfma_f32_16x16x32_bf16 v[30:33], v[238:241], v[206:209], v[30:33]
	v_mfma_f32_16x16x32_bf16 v[22:25], v[230:233], v[214:217], v[22:25]
	v_mfma_f32_16x16x32_bf16 v[14:17], v[238:241], v[214:217], v[14:17]
	v_mfma_f32_16x16x32_bf16 v[6:9], v[230:233], v[222:225], v[6:9]
	v_mfma_f32_16x16x32_bf16 v[2:5], v[238:241], v[222:225], v[2:5]
	v_mfma_f32_16x16x32_bf16 v[54:57], v[234:237], v[184:187], v[54:57]
	v_mfma_f32_16x16x32_bf16 v[46:49], v[242:245], v[184:187], v[46:49]
	v_mfma_f32_16x16x32_bf16 v[38:41], v[234:237], v[210:213], v[38:41]
	v_mfma_f32_16x16x32_bf16 v[30:33], v[242:245], v[210:213], v[30:33]
	v_mfma_f32_16x16x32_bf16 v[22:25], v[234:237], v[218:221], v[22:25]
	v_mfma_f32_16x16x32_bf16 v[14:17], v[242:245], v[218:221], v[14:17]
	v_mfma_f32_16x16x32_bf16 v[6:9], v[234:237], v[226:229], v[6:9]
	v_mfma_f32_16x16x32_bf16 v[2:5], v[242:245], v[226:229], v[2:5]
	s_barrier
	s_add_i32 s51, s51, 2
	s_add_u32 s40, s40, 0x100
	s_addc_u32 s41, s41, 0
	s_cmp_gt_u32 s51, 41
	s_mov_b64 s[24:25], s[22:23]
	s_cbranch_scc0 .LBB0_331
	v_lshl_or_b32 v140, s50, 8, v145
	v_lshl_add_u32 v164, s49, 8, v143
	v_ashrrev_i32_e32 v141, 31, v140
	v_ashrrev_i32_e32 v165, 31, v164
	v_lshl_add_u64 v[166:167], v[140:141], 1, s[20:21]
	v_lshlrev_b64 v[140:141], 11, v[164:165]
	v_lshl_add_u64 v[140:141], v[166:167], 0, v[140:141]
	v_pk_add_f32 v[128:129], v[128:129], 0 op_sel_hi:[1,0]
	v_pk_add_f32 v[126:127], v[126:127], 0 op_sel_hi:[1,0]
	v_pk_add_f32 v[168:169], v[124:125], 0 op_sel_hi:[1,0]
	v_pk_add_f32 v[124:125], v[122:123], 0 op_sel_hi:[1,0]
	v_cvt_pk_bf16_f32 v122, v126, v127
	v_cvt_pk_bf16_f32 v123, v128, v129
	v_pk_add_f32 v[118:119], v[118:119], 0 op_sel_hi:[1,0]
	v_cvt_pk_bf16_f32 v124, v124, v125
	v_cvt_pk_bf16_f32 v125, v168, v169
	global_store_dwordx4 v[140:141], v[122:125], off
	v_pk_add_f32 v[120:121], v[120:121], 0 op_sel_hi:[1,0]
	v_pk_add_f32 v[114:115], v[114:115], 0 op_sel_hi:[1,0]
	v_pk_add_f32 v[122:123], v[112:113], 0 op_sel_hi:[1,0]
	v_pk_add_f32 v[112:113], v[110:111], 0 op_sel_hi:[1,0]
	v_cvt_pk_bf16_f32 v110, v118, v119
	v_cvt_pk_bf16_f32 v111, v120, v121
	v_pk_add_f32 v[102:103], v[102:103], 0 op_sel_hi:[1,0]
	v_cvt_pk_bf16_f32 v112, v112, v113
	v_cvt_pk_bf16_f32 v113, v122, v123
	global_store_dwordx4 v[140:141], v[110:113], off offset:256
	v_pk_add_f32 v[104:105], v[104:105], 0 op_sel_hi:[1,0]
	v_pk_add_f32 v[98:99], v[98:99], 0 op_sel_hi:[1,0]
	v_or_b32_e32 v110, 16, v164
	v_ashrrev_i32_e32 v111, 31, v110
	v_lshlrev_b64 v[110:111], 11, v[110:111]
	v_lshl_add_u64 v[110:111], v[166:167], 0, v[110:111]
	v_pk_add_f32 v[112:113], v[116:117], 0 op_sel_hi:[1,0]
	v_pk_add_f32 v[116:117], v[108:109], 0 op_sel_hi:[1,0]
	v_pk_add_f32 v[108:109], v[106:107], 0 op_sel_hi:[1,0]
	v_cvt_pk_bf16_f32 v106, v114, v115
	v_cvt_pk_bf16_f32 v107, v112, v113
	v_pk_add_f32 v[86:87], v[86:87], 0 op_sel_hi:[1,0]
	v_cvt_pk_bf16_f32 v108, v108, v109
	v_cvt_pk_bf16_f32 v109, v116, v117
	global_store_dwordx4 v[110:111], v[106:109], off
	v_pk_add_f32 v[88:89], v[88:89], 0 op_sel_hi:[1,0]
	v_pk_add_f32 v[82:83], v[82:83], 0 op_sel_hi:[1,0]
	v_pk_add_f32 v[106:107], v[96:97], 0 op_sel_hi:[1,0]
	v_pk_add_f32 v[96:97], v[94:95], 0 op_sel_hi:[1,0]
	v_cvt_pk_bf16_f32 v94, v102, v103
	v_cvt_pk_bf16_f32 v95, v104, v105
	v_pk_add_f32 v[72:73], v[72:73], 0 op_sel_hi:[1,0]
	v_cvt_pk_bf16_f32 v96, v96, v97
	v_cvt_pk_bf16_f32 v97, v106, v107
	global_store_dwordx4 v[110:111], v[94:97], off offset:256
	v_pk_add_f32 v[70:71], v[70:71], 0 op_sel_hi:[1,0]
	v_pk_add_f32 v[62:63], v[62:63], 0 op_sel_hi:[1,0]
	v_or_b32_e32 v94, 32, v164
	v_ashrrev_i32_e32 v95, 31, v94
	v_lshlrev_b64 v[94:95], 11, v[94:95]
	v_lshl_add_u64 v[94:95], v[166:167], 0, v[94:95]
	v_pk_add_f32 v[96:97], v[100:101], 0 op_sel_hi:[1,0]
	v_pk_add_f32 v[100:101], v[92:93], 0 op_sel_hi:[1,0]
	v_pk_add_f32 v[92:93], v[90:91], 0 op_sel_hi:[1,0]
	v_cvt_pk_bf16_f32 v90, v98, v99
	v_cvt_pk_bf16_f32 v91, v96, v97
	v_pk_add_f32 v[64:65], v[64:65], 0 op_sel_hi:[1,0]
	v_cvt_pk_bf16_f32 v92, v92, v93
	v_cvt_pk_bf16_f32 v93, v100, v101
	global_store_dwordx4 v[94:95], v[90:93], off
	s_mov_b64 s[22:23], 0x40000
	v_pk_add_f32 v[56:57], v[56:57], 0 op_sel_hi:[1,0]
	v_pk_add_f32 v[90:91], v[80:81], 0 op_sel_hi:[1,0]
	v_pk_add_f32 v[80:81], v[78:79], 0 op_sel_hi:[1,0]
	v_cvt_pk_bf16_f32 v78, v86, v87
	v_cvt_pk_bf16_f32 v79, v88, v89
	v_pk_add_f32 v[54:55], v[54:55], 0 op_sel_hi:[1,0]
	v_cvt_pk_bf16_f32 v80, v80, v81
	v_cvt_pk_bf16_f32 v81, v90, v91
	global_store_dwordx4 v[94:95], v[78:81], off offset:256
	v_pk_add_f32 v[50:51], v[50:51], 0 op_sel_hi:[1,0]
	v_pk_add_f32 v[40:41], v[40:41], 0 op_sel_hi:[1,0]
	v_or_b32_e32 v78, 48, v164
	v_ashrrev_i32_e32 v79, 31, v78
	v_lshlrev_b64 v[78:79], 11, v[78:79]
	v_lshl_add_u64 v[78:79], v[166:167], 0, v[78:79]
	v_pk_add_f32 v[80:81], v[84:85], 0 op_sel_hi:[1,0]
	v_pk_add_f32 v[84:85], v[76:77], 0 op_sel_hi:[1,0]
	v_pk_add_f32 v[76:77], v[74:75], 0 op_sel_hi:[1,0]
	v_cvt_pk_bf16_f32 v74, v82, v83
	v_cvt_pk_bf16_f32 v75, v80, v81
	v_pk_add_f32 v[38:39], v[38:39], 0 op_sel_hi:[1,0]
	v_cvt_pk_bf16_f32 v76, v76, v77
	v_cvt_pk_bf16_f32 v77, v84, v85
	global_store_dwordx4 v[78:79], v[74:77], off
	v_pk_add_f32 v[34:35], v[34:35], 0 op_sel_hi:[1,0]
	v_pk_add_f32 v[24:25], v[24:25], 0 op_sel_hi:[1,0]
	v_pk_add_f32 v[74:75], v[68:69], 0 op_sel_hi:[1,0]
	v_pk_add_f32 v[68:69], v[66:67], 0 op_sel_hi:[1,0]
	v_cvt_pk_bf16_f32 v66, v70, v71
	v_cvt_pk_bf16_f32 v67, v72, v73
	v_pk_add_f32 v[22:23], v[22:23], 0 op_sel_hi:[1,0]
	v_cvt_pk_bf16_f32 v68, v68, v69
	v_cvt_pk_bf16_f32 v69, v74, v75
	global_store_dwordx4 v[78:79], v[66:69], off offset:256
	v_pk_add_f32 v[18:19], v[18:19], 0 op_sel_hi:[1,0]
	s_mov_b32 s50, s47
	v_pk_add_f32 v[68:69], v[60:61], 0 op_sel_hi:[1,0]
	v_pk_add_f32 v[60:61], v[58:59], 0 op_sel_hi:[1,0]
	v_cvt_pk_bf16_f32 v58, v62, v63
	v_add_co_u32_e32 v62, vcc, s67, v140
	v_cvt_pk_bf16_f32 v59, v64, v65
	v_cvt_pk_bf16_f32 v60, v60, v61
	v_cvt_pk_bf16_f32 v61, v68, v69
	v_lshl_add_u64 v[66:67], v[140:141], 0, s[22:23]
	s_nop 0
	v_addc_co_u32_e32 v63, vcc, 0, v141, vcc
	global_store_dwordx4 v[62:63], v[58:61], off
	s_mov_b64 s[22:23], 0x48000
	s_mov_b32 s49, s48
	v_pk_add_f32 v[58:59], v[48:49], 0 op_sel_hi:[1,0]
	v_pk_add_f32 v[48:49], v[46:47], 0 op_sel_hi:[1,0]
	v_cvt_pk_bf16_f32 v46, v54, v55
	v_cvt_pk_bf16_f32 v47, v56, v57
	s_mov_b64 s[24:25], s[2:3]
	v_cvt_pk_bf16_f32 v48, v48, v49
	v_cvt_pk_bf16_f32 v49, v58, v59
	global_store_dwordx4 v[66:67], v[46:49], off offset:256
	v_pk_add_f32 v[8:9], v[8:9], 0 op_sel_hi:[1,0]
	v_pk_add_f32 v[6:7], v[6:7], 0 op_sel_hi:[1,0]
	v_pk_add_f32 v[48:49], v[52:53], 0 op_sel_hi:[1,0]
	v_pk_add_f32 v[52:53], v[44:45], 0 op_sel_hi:[1,0]
	v_pk_add_f32 v[44:45], v[42:43], 0 op_sel_hi:[1,0]
	v_cvt_pk_bf16_f32 v42, v50, v51
	v_cvt_pk_bf16_f32 v43, v48, v49
	v_add_co_u32_e32 v48, vcc, s68, v140
	v_cvt_pk_bf16_f32 v44, v44, v45
	v_cvt_pk_bf16_f32 v45, v52, v53
	v_lshl_add_u64 v[46:47], v[140:141], 0, s[22:23]
	s_nop 0
	v_addc_co_u32_e32 v49, vcc, 0, v141, vcc
	global_store_dwordx4 v[48:49], v[42:45], off
	s_mov_b64 s[22:23], 0x50000
	s_nop 0
	v_pk_add_f32 v[42:43], v[32:33], 0 op_sel_hi:[1,0]
	v_pk_add_f32 v[32:33], v[30:31], 0 op_sel_hi:[1,0]
	v_cvt_pk_bf16_f32 v30, v38, v39
	v_cvt_pk_bf16_f32 v31, v40, v41
	s_nop 0
	v_cvt_pk_bf16_f32 v32, v32, v33
	v_cvt_pk_bf16_f32 v33, v42, v43
	global_store_dwordx4 v[46:47], v[30:33], off offset:256
	s_nop 1
	v_lshl_add_u64 v[30:31], v[140:141], 0, s[22:23]
	v_pk_add_f32 v[32:33], v[36:37], 0 op_sel_hi:[1,0]
	s_mov_b32 s22, 0x50000
	v_pk_add_f32 v[36:37], v[28:29], 0 op_sel_hi:[1,0]
	v_pk_add_f32 v[28:29], v[26:27], 0 op_sel_hi:[1,0]
	v_cvt_pk_bf16_f32 v26, v34, v35
	v_cvt_pk_bf16_f32 v27, v32, v33
	v_add_co_u32_e32 v32, vcc, s22, v140
	v_cvt_pk_bf16_f32 v28, v28, v29
	v_cvt_pk_bf16_f32 v29, v36, v37
	s_mov_b64 s[22:23], 0x58000
	s_nop 0
	v_addc_co_u32_e32 v33, vcc, 0, v141, vcc
	global_store_dwordx4 v[32:33], v[26:29], off
	s_nop 1
	v_pk_add_f32 v[26:27], v[16:17], 0 op_sel_hi:[1,0]
	v_pk_add_f32 v[16:17], v[14:15], 0 op_sel_hi:[1,0]
	v_cvt_pk_bf16_f32 v14, v22, v23
	v_cvt_pk_bf16_f32 v15, v24, v25
	s_nop 0
	v_cvt_pk_bf16_f32 v16, v16, v17
	v_cvt_pk_bf16_f32 v17, v26, v27
	global_store_dwordx4 v[30:31], v[14:17], off offset:256
	s_nop 1
	v_lshl_add_u64 v[14:15], v[140:141], 0, s[22:23]
	v_pk_add_f32 v[16:17], v[20:21], 0 op_sel_hi:[1,0]
	s_mov_b32 s22, 0x58000
	v_pk_add_f32 v[20:21], v[12:13], 0 op_sel_hi:[1,0]
	v_pk_add_f32 v[12:13], v[10:11], 0 op_sel_hi:[1,0]
	v_cvt_pk_bf16_f32 v10, v18, v19
	v_cvt_pk_bf16_f32 v11, v16, v17
	v_add_co_u32_e32 v16, vcc, s22, v140
	v_cvt_pk_bf16_f32 v12, v12, v13
	v_cvt_pk_bf16_f32 v13, v20, v21
	s_mov_b64 s[22:23], s[0:1]
	s_nop 0
	v_addc_co_u32_e32 v17, vcc, 0, v141, vcc
	global_store_dwordx4 v[16:17], v[10:13], off
	s_and_b64 vcc, exec, s[38:39]
	s_nop 0
	v_pk_add_f32 v[10:11], v[4:5], 0 op_sel_hi:[1,0]
	v_pk_add_f32 v[4:5], v[2:3], 0 op_sel_hi:[1,0]
	v_cvt_pk_bf16_f32 v2, v6, v7
	v_cvt_pk_bf16_f32 v3, v8, v9
	s_nop 0
	v_cvt_pk_bf16_f32 v4, v4, v5
	v_cvt_pk_bf16_f32 v5, v10, v11
	global_store_dwordx4 v[14:15], v[2:5], off offset:256
	s_cbranch_vccz .LBB0_320
	s_waitcnt vmcnt(16)
	s_cmpk_gt_u32 s30, 0xff
	s_cbranch_scc1 .LBB0_335
	s_barrier

.Lkprio_1:
.LBB0_360:
	s_add_u32 s44, s42, 0xfffc0080
	s_addc_u32 s45, s43, -1
	s_add_i32 s63, 0, 0x10000
	v_add_u32_e32 v0, s63, v206
	ds_read_b128 v[82:85], v0
	ds_read_b128 v[86:89], v0 offset:1024
	ds_read_b128 v[90:93], v0 offset:2048
	ds_read_b128 v[94:97], v0 offset:3072
	s_cmp_eq_u32 s62, 12
	s_cselect_b32 s47, s1, s45
	s_cselect_b32 s46, s3, s44
	s_cselect_b32 s45, s31, s61
	s_cselect_b32 s44, s35, s60
	v_lshl_add_u64 v[230:231], s[42:43], 0, v[174:175]
	s_add_i32 m0, s51, 0xc000
	ds_read_b128 v[176:179], v208
	ds_read_b128 v[180:183], v208 offset:1024
	ds_read_b128 v[184:187], v208 offset:2048
	ds_read_b128 v[210:213], v208 offset:3072
	ds_read_b128 v[214:217], v208 offset:4096
	ds_read_b128 v[218:221], v208 offset:5120
	ds_read_b128 v[222:225], v208 offset:6144
	ds_read_b128 v[226:229], v208 offset:7168
	global_load_lds_dwordx4 v[230:231], off
	s_add_i32 m0, s51, 0xe000
	v_lshl_add_u64 v[230:231], s[42:43], 0, v[172:173]
	global_load_lds_dwordx4 v[230:231], off
	s_waitcnt lgkmcnt(8)
	s_barrier
	s_waitcnt lgkmcnt(7)
	v_mfma_f32_16x16x32_bf16 v[142:145], v[82:85], v[176:179], v[142:145]
	v_mfma_f32_16x16x32_bf16 v[138:141], v[90:93], v[176:179], v[138:141]
	s_waitcnt lgkmcnt(5)
	v_mfma_f32_16x16x32_bf16 v[126:129], v[82:85], v[184:187], v[126:129]
	v_mfma_f32_16x16x32_bf16 v[122:125], v[90:93], v[184:187], v[122:125]
	s_waitcnt lgkmcnt(3)
	v_mfma_f32_16x16x32_bf16 v[110:113], v[82:85], v[214:217], v[110:113]
	v_mfma_f32_16x16x32_bf16 v[106:109], v[90:93], v[214:217], v[106:109]
	s_waitcnt lgkmcnt(1)
	v_mfma_f32_16x16x32_bf16 v[78:81], v[82:85], v[222:225], v[78:81]
	v_mfma_f32_16x16x32_bf16 v[74:77], v[90:93], v[222:225], v[74:77]
	v_mfma_f32_16x16x32_bf16 v[142:145], v[86:89], v[180:183], v[142:145]
	v_mfma_f32_16x16x32_bf16 v[138:141], v[94:97], v[180:183], v[138:141]
	v_mfma_f32_16x16x32_bf16 v[126:129], v[86:89], v[210:213], v[126:129]
	v_mfma_f32_16x16x32_bf16 v[122:125], v[94:97], v[210:213], v[122:125]
	v_mfma_f32_16x16x32_bf16 v[110:113], v[86:89], v[218:221], v[110:113]
	v_mfma_f32_16x16x32_bf16 v[106:109], v[94:97], v[218:221], v[106:109]
	s_waitcnt lgkmcnt(0)
	v_mfma_f32_16x16x32_bf16 v[78:81], v[86:89], v[226:229], v[78:81]
	v_mfma_f32_16x16x32_bf16 v[74:77], v[94:97], v[226:229], v[74:77]
	s_barrier
	s_add_i32 s66, 0, 0x14000
	s_add_i32 s63, s63, s50
	v_add_u32_e32 v0, s66, v206
	v_lshl_add_u64 v[246:247], s[44:45], 0, v[164:165]
	s_mov_b32 m0, s63
	ds_read_b128 v[230:233], v0
	ds_read_b128 v[234:237], v0 offset:1024
	ds_read_b128 v[238:241], v0 offset:2048
	ds_read_b128 v[242:245], v0 offset:3072
	global_load_lds_dwordx4 v[246:247], off
	s_add_i32 m0, s63, 0x2000
	v_lshl_add_u64 v[248:249], s[44:45], 0, v[168:169]
	global_load_lds_dwordx4 v[248:249], off
	s_barrier
	s_waitcnt lgkmcnt(3)
	v_mfma_f32_16x16x32_bf16 v[134:137], v[230:233], v[176:179], v[134:137]
	s_waitcnt lgkmcnt(1)
	v_mfma_f32_16x16x32_bf16 v[130:133], v[238:241], v[176:179], v[130:133]
	v_mfma_f32_16x16x32_bf16 v[118:121], v[230:233], v[184:187], v[118:121]
	v_mfma_f32_16x16x32_bf16 v[114:117], v[238:241], v[184:187], v[114:117]
	v_mfma_f32_16x16x32_bf16 v[102:105], v[230:233], v[214:217], v[102:105]
	v_mfma_f32_16x16x32_bf16 v[98:101], v[238:241], v[214:217], v[98:101]
	v_mfma_f32_16x16x32_bf16 v[70:73], v[230:233], v[222:225], v[70:73]
	v_mfma_f32_16x16x32_bf16 v[66:69], v[238:241], v[222:225], v[66:69]
	v_mfma_f32_16x16x32_bf16 v[134:137], v[234:237], v[180:183], v[134:137]
	s_waitcnt lgkmcnt(0)
	v_mfma_f32_16x16x32_bf16 v[130:133], v[242:245], v[180:183], v[130:133]
	v_mfma_f32_16x16x32_bf16 v[118:121], v[234:237], v[210:213], v[118:121]
	v_mfma_f32_16x16x32_bf16 v[114:117], v[242:245], v[210:213], v[114:117]
	v_mfma_f32_16x16x32_bf16 v[102:105], v[234:237], v[218:221], v[102:105]
	v_mfma_f32_16x16x32_bf16 v[98:101], v[242:245], v[218:221], v[98:101]
	v_mfma_f32_16x16x32_bf16 v[70:73], v[234:237], v[226:229], v[70:73]
	v_mfma_f32_16x16x32_bf16 v[66:69], v[242:245], v[226:229], v[66:69]
	s_barrier
	s_mov_b32 m0, s51
	v_lshl_add_u64 v[250:251], s[46:47], 0, v[162:163]
	ds_read_b128 v[176:179], v208 offset:16384
	ds_read_b128 v[180:183], v208 offset:17408
	ds_read_b128 v[184:187], v208 offset:18432
	ds_read_b128 v[210:213], v208 offset:19456
	ds_read_b128 v[214:217], v208 offset:20480
	ds_read_b128 v[218:221], v208 offset:21504
	ds_read_b128 v[222:225], v208 offset:22528
	ds_read_b128 v[226:229], v208 offset:23552
	global_load_lds_dwordx4 v[250:251], off
	s_mov_b32 m0, s52
	v_lshl_add_u64 v[252:253], s[46:47], 0, v[166:167]
	global_load_lds_dwordx4 v[252:253], off
	s_barrier
	s_waitcnt lgkmcnt(7)
	v_mfma_f32_16x16x32_bf16 v[62:65], v[82:85], v[176:179], v[62:65]
	v_mfma_f32_16x16x32_bf16 v[58:61], v[90:93], v[176:179], v[58:61]
	s_waitcnt lgkmcnt(5)
	v_mfma_f32_16x16x32_bf16 v[46:49], v[82:85], v[184:187], v[46:49]
	v_mfma_f32_16x16x32_bf16 v[42:45], v[90:93], v[184:187], v[42:45]
	s_waitcnt lgkmcnt(3)
	v_mfma_f32_16x16x32_bf16 v[30:33], v[82:85], v[214:217], v[30:33]
	v_mfma_f32_16x16x32_bf16 v[26:29], v[90:93], v[214:217], v[26:29]
	s_waitcnt lgkmcnt(1)
	v_mfma_f32_16x16x32_bf16 v[14:17], v[82:85], v[222:225], v[14:17]
	v_mfma_f32_16x16x32_bf16 v[10:13], v[90:93], v[222:225], v[10:13]
	v_mfma_f32_16x16x32_bf16 v[62:65], v[86:89], v[180:183], v[62:65]
	v_mfma_f32_16x16x32_bf16 v[58:61], v[94:97], v[180:183], v[58:61]
	v_mfma_f32_16x16x32_bf16 v[46:49], v[86:89], v[210:213], v[46:49]
	v_mfma_f32_16x16x32_bf16 v[42:45], v[94:97], v[210:213], v[42:45]
	v_mfma_f32_16x16x32_bf16 v[30:33], v[86:89], v[218:221], v[30:33]
	v_mfma_f32_16x16x32_bf16 v[26:29], v[94:97], v[218:221], v[26:29]
	s_waitcnt lgkmcnt(0)
	v_mfma_f32_16x16x32_bf16 v[14:17], v[86:89], v[226:229], v[14:17]
	v_mfma_f32_16x16x32_bf16 v[10:13], v[94:97], v[226:229], v[10:13]
	s_barrier
	s_add_u32 s64, s44, 0x40000
	s_addc_u32 s65, s45, 0
	s_add_i32 s63, s66, s50
	s_mov_b32 m0, s63
	v_lshl_add_u64 v[82:83], s[64:65], 0, v[164:165]
	global_load_lds_dwordx4 v[82:83], off
	s_add_i32 m0, s63, 0x2000
	v_lshl_add_u64 v[82:83], s[64:65], 0, v[168:169]
	global_load_lds_dwordx4 v[82:83], off
	s_waitcnt vmcnt(6)
	s_barrier
	v_mfma_f32_16x16x32_bf16 v[54:57], v[230:233], v[176:179], v[54:57]
	v_mfma_f32_16x16x32_bf16 v[50:53], v[238:241], v[176:179], v[50:53]
	v_mfma_f32_16x16x32_bf16 v[38:41], v[230:233], v[184:187], v[38:41]
	v_mfma_f32_16x16x32_bf16 v[34:37], v[238:241], v[184:187], v[34:37]
	v_mfma_f32_16x16x32_bf16 v[22:25], v[230:233], v[214:217], v[22:25]
	v_mfma_f32_16x16x32_bf16 v[18:21], v[238:241], v[214:217], v[18:21]
	v_mfma_f32_16x16x32_bf16 v[6:9], v[230:233], v[222:225], v[6:9]
	v_mfma_f32_16x16x32_bf16 v[2:5], v[238:241], v[222:225], v[2:5]
	v_mfma_f32_16x16x32_bf16 v[54:57], v[234:237], v[180:183], v[54:57]
	v_mfma_f32_16x16x32_bf16 v[50:53], v[242:245], v[180:183], v[50:53]
	v_mfma_f32_16x16x32_bf16 v[38:41], v[234:237], v[210:213], v[38:41]
	v_mfma_f32_16x16x32_bf16 v[34:37], v[242:245], v[210:213], v[34:37]
	v_mfma_f32_16x16x32_bf16 v[22:25], v[234:237], v[218:221], v[22:25]
	v_mfma_f32_16x16x32_bf16 v[18:21], v[242:245], v[218:221], v[18:21]
	v_mfma_f32_16x16x32_bf16 v[6:9], v[234:237], v[226:229], v[6:9]
	v_mfma_f32_16x16x32_bf16 v[2:5], v[242:245], v[226:229], v[2:5]
	s_barrier
	s_add_i32 s63, 0, 0x18000
	v_add_u32_e32 v0, s63, v206
	ds_read_b128 v[82:85], v0
	ds_read_b128 v[86:89], v0 offset:1024
	ds_read_b128 v[90:93], v0 offset:2048
	ds_read_b128 v[94:97], v0 offset:3072
	s_add_u32 s46, s46, 0x40000
	s_addc_u32 s47, s47, 0
	s_mov_b32 m0, s53
	v_lshl_add_u64 v[230:231], s[46:47], 0, v[162:163]
	ds_read_b128 v[176:179], v208 offset:32768
	ds_read_b128 v[180:183], v208 offset:33792
	ds_read_b128 v[184:187], v208 offset:34816
	ds_read_b128 v[210:213], v208 offset:35840
	ds_read_b128 v[214:217], v208 offset:36864
	ds_read_b128 v[218:221], v208 offset:37888
	ds_read_b128 v[222:225], v208 offset:38912
	ds_read_b128 v[226:229], v208 offset:39936
	global_load_lds_dwordx4 v[230:231], off
	s_mov_b32 m0, s54
	v_lshl_add_u64 v[230:231], s[46:47], 0, v[166:167]
	global_load_lds_dwordx4 v[230:231], off
	s_waitcnt lgkmcnt(8)
	s_barrier
	s_waitcnt lgkmcnt(7)
	v_mfma_f32_16x16x32_bf16 v[142:145], v[82:85], v[176:179], v[142:145]
	v_mfma_f32_16x16x32_bf16 v[138:141], v[90:93], v[176:179], v[138:141]
	s_waitcnt lgkmcnt(5)
	v_mfma_f32_16x16x32_bf16 v[126:129], v[82:85], v[184:187], v[126:129]
	v_mfma_f32_16x16x32_bf16 v[122:125], v[90:93], v[184:187], v[122:125]
	s_waitcnt lgkmcnt(3)
	v_mfma_f32_16x16x32_bf16 v[110:113], v[82:85], v[214:217], v[110:113]
	v_mfma_f32_16x16x32_bf16 v[106:109], v[90:93], v[214:217], v[106:109]
	s_waitcnt lgkmcnt(1)
	v_mfma_f32_16x16x32_bf16 v[78:81], v[82:85], v[222:225], v[78:81]
	v_mfma_f32_16x16x32_bf16 v[74:77], v[90:93], v[222:225], v[74:77]
	v_mfma_f32_16x16x32_bf16 v[142:145], v[86:89], v[180:183], v[142:145]
	v_mfma_f32_16x16x32_bf16 v[138:141], v[94:97], v[180:183], v[138:141]
	v_mfma_f32_16x16x32_bf16 v[126:129], v[86:89], v[210:213], v[126:129]
	v_mfma_f32_16x16x32_bf16 v[122:125], v[94:97], v[210:213], v[122:125]
	v_mfma_f32_16x16x32_bf16 v[110:113], v[86:89], v[218:221], v[110:113]
	v_mfma_f32_16x16x32_bf16 v[106:109], v[94:97], v[218:221], v[106:109]
	s_waitcnt lgkmcnt(0)
	v_mfma_f32_16x16x32_bf16 v[78:81], v[86:89], v[226:229], v[78:81]
	v_mfma_f32_16x16x32_bf16 v[74:77], v[94:97], v[226:229], v[74:77]
	s_barrier
	s_add_i32 s46, 0, 0x1c000
	s_add_i32 s47, s63, s50
	v_add_u32_e32 v0, s46, v206
	v_lshl_add_u64 v[246:247], v[246:247], 0, s[94:95]
	s_mov_b32 m0, s47
	ds_read_b128 v[230:233], v0
	ds_read_b128 v[234:237], v0 offset:1024
	ds_read_b128 v[238:241], v0 offset:2048
	ds_read_b128 v[242:245], v0 offset:3072
	global_load_lds_dwordx4 v[246:247], off
	s_add_i32 m0, s47, 0x2000
	v_lshl_add_u64 v[246:247], v[248:249], 0, s[94:95]
	global_load_lds_dwordx4 v[246:247], off
	s_barrier
	s_waitcnt lgkmcnt(3)
	v_mfma_f32_16x16x32_bf16 v[134:137], v[230:233], v[176:179], v[134:137]
	s_waitcnt lgkmcnt(1)
	v_mfma_f32_16x16x32_bf16 v[130:133], v[238:241], v[176:179], v[130:133]
	v_mfma_f32_16x16x32_bf16 v[118:121], v[230:233], v[184:187], v[118:121]
	v_mfma_f32_16x16x32_bf16 v[114:117], v[238:241], v[184:187], v[114:117]
	v_mfma_f32_16x16x32_bf16 v[102:105], v[230:233], v[214:217], v[102:105]
	v_mfma_f32_16x16x32_bf16 v[98:101], v[238:241], v[214:217], v[98:101]
	v_mfma_f32_16x16x32_bf16 v[70:73], v[230:233], v[222:225], v[70:73]
	v_mfma_f32_16x16x32_bf16 v[66:69], v[238:241], v[222:225], v[66:69]
	v_mfma_f32_16x16x32_bf16 v[134:137], v[234:237], v[180:183], v[134:137]
	s_waitcnt lgkmcnt(0)
	v_mfma_f32_16x16x32_bf16 v[130:133], v[242:245], v[180:183], v[130:133]
	v_mfma_f32_16x16x32_bf16 v[118:121], v[234:237], v[210:213], v[118:121]
	v_mfma_f32_16x16x32_bf16 v[114:117], v[242:245], v[210:213], v[114:117]
	v_mfma_f32_16x16x32_bf16 v[102:105], v[234:237], v[218:221], v[102:105]
	v_mfma_f32_16x16x32_bf16 v[98:101], v[242:245], v[218:221], v[98:101]
	v_mfma_f32_16x16x32_bf16 v[70:73], v[234:237], v[226:229], v[70:73]
	v_mfma_f32_16x16x32_bf16 v[66:69], v[242:245], v[226:229], v[66:69]
	s_barrier
	s_mov_b32 m0, s56
	v_lshl_add_u64 v[246:247], v[250:251], 0, s[94:95]
	ds_read_b128 v[176:179], v208 offset:49152
	ds_read_b128 v[180:183], v208 offset:50176
	ds_read_b128 v[184:187], v208 offset:51200
	ds_read_b128 v[210:213], v208 offset:52224
	ds_read_b128 v[214:217], v208 offset:53248
	ds_read_b128 v[218:221], v208 offset:54272
	ds_read_b128 v[222:225], v208 offset:55296
	ds_read_b128 v[226:229], v208 offset:56320
	global_load_lds_dwordx4 v[246:247], off
	s_mov_b32 m0, s57
	v_lshl_add_u64 v[246:247], v[252:253], 0, s[94:95]
	global_load_lds_dwordx4 v[246:247], off
	s_barrier
	s_waitcnt lgkmcnt(7)
	v_mfma_f32_16x16x32_bf16 v[62:65], v[82:85], v[176:179], v[62:65]
	v_mfma_f32_16x16x32_bf16 v[58:61], v[90:93], v[176:179], v[58:61]
	s_waitcnt lgkmcnt(5)
	v_mfma_f32_16x16x32_bf16 v[46:49], v[82:85], v[184:187], v[46:49]
	v_mfma_f32_16x16x32_bf16 v[42:45], v[90:93], v[184:187], v[42:45]
	s_waitcnt lgkmcnt(3)
	v_mfma_f32_16x16x32_bf16 v[30:33], v[82:85], v[214:217], v[30:33]
	v_mfma_f32_16x16x32_bf16 v[26:29], v[90:93], v[214:217], v[26:29]
	s_waitcnt lgkmcnt(1)
	v_mfma_f32_16x16x32_bf16 v[14:17], v[82:85], v[222:225], v[14:17]
	v_mfma_f32_16x16x32_bf16 v[10:13], v[90:93], v[222:225], v[10:13]
	v_mfma_f32_16x16x32_bf16 v[62:65], v[86:89], v[180:183], v[62:65]
	v_mfma_f32_16x16x32_bf16 v[58:61], v[94:97], v[180:183], v[58:61]
	v_mfma_f32_16x16x32_bf16 v[46:49], v[86:89], v[210:213], v[46:49]
	v_mfma_f32_16x16x32_bf16 v[42:45], v[94:97], v[210:213], v[42:45]
	v_mfma_f32_16x16x32_bf16 v[30:33], v[86:89], v[218:221], v[30:33]
	v_mfma_f32_16x16x32_bf16 v[26:29], v[94:97], v[218:221], v[26:29]
	s_waitcnt lgkmcnt(0)
	v_mfma_f32_16x16x32_bf16 v[14:17], v[86:89], v[226:229], v[14:17]
	v_mfma_f32_16x16x32_bf16 v[10:13], v[94:97], v[226:229], v[10:13]
	s_barrier
	s_add_u32 s44, s44, 0x40080
	s_addc_u32 s45, s45, 0
	s_add_i32 s46, s46, s50
	s_mov_b32 m0, s46
	v_lshl_add_u64 v[82:83], s[44:45], 0, v[164:165]
	global_load_lds_dwordx4 v[82:83], off
	s_add_i32 m0, s46, 0x2000
	v_lshl_add_u64 v[82:83], s[44:45], 0, v[168:169]
	global_load_lds_dwordx4 v[82:83], off
	s_waitcnt vmcnt(6)
	s_barrier
	v_mfma_f32_16x16x32_bf16 v[54:57], v[230:233], v[176:179], v[54:57]
	v_mfma_f32_16x16x32_bf16 v[50:53], v[238:241], v[176:179], v[50:53]
	v_mfma_f32_16x16x32_bf16 v[38:41], v[230:233], v[184:187], v[38:41]
	v_mfma_f32_16x16x32_bf16 v[34:37], v[238:241], v[184:187], v[34:37]
	v_mfma_f32_16x16x32_bf16 v[22:25], v[230:233], v[214:217], v[22:25]
	v_mfma_f32_16x16x32_bf16 v[18:21], v[238:241], v[214:217], v[18:21]
	v_mfma_f32_16x16x32_bf16 v[6:9], v[230:233], v[222:225], v[6:9]
	v_mfma_f32_16x16x32_bf16 v[2:5], v[238:241], v[222:225], v[2:5]
	v_mfma_f32_16x16x32_bf16 v[54:57], v[234:237], v[180:183], v[54:57]
	v_mfma_f32_16x16x32_bf16 v[50:53], v[242:245], v[180:183], v[50:53]
	v_mfma_f32_16x16x32_bf16 v[38:41], v[234:237], v[210:213], v[38:41]
	v_mfma_f32_16x16x32_bf16 v[34:37], v[242:245], v[210:213], v[34:37]
	v_mfma_f32_16x16x32_bf16 v[22:25], v[234:237], v[218:221], v[22:25]
	v_mfma_f32_16x16x32_bf16 v[18:21], v[242:245], v[218:221], v[18:21]
	v_mfma_f32_16x16x32_bf16 v[6:9], v[234:237], v[226:229], v[6:9]
	v_mfma_f32_16x16x32_bf16 v[2:5], v[242:245], v[226:229], v[2:5]
	s_barrier
	s_add_i32 s62, s62, 2
	s_add_u32 s60, s60, 0x100
	s_addc_u32 s61, s61, 0
	s_add_u32 s42, s42, 0x100
	s_addc_u32 s43, s43, 0
	s_cmp_gt_u32 s62, 13
	s_cbranch_scc0 .LBB0_360
	v_lshl_or_b32 v180, s0, 8, v207
	v_ashrrev_i32_e32 v181, 31, v180
	v_mov_b32_e32 v86, 0
	v_cndmask_b32_e64 v0, 0, 1, s[26:27]
	v_lshl_add_u64 v[176:177], v[180:181], 2, s[22:23]
	v_cmp_ne_u32_e64 s[0:1], 1, v0
	s_andn2_b64 vcc, exec, s[26:27]
	v_mov_b32_e32 v94, 0
	v_mov_b32_e32 v95, v86
	v_mov_b32_e32 v96, 0
	v_mov_b32_e32 v97, 0
	s_cbranch_vccnz .LBB0_363
	global_load_dwordx4 v[94:97], v[176:177], off

.Lkprio_0:
.LBB0_586:
	s_add_u32 s22, s20, 0xfffc0080
	s_addc_u32 s23, s21, -1
	s_add_i32 s48, 0, 0x10000
	v_add_u32_e32 v140, s48, v143
	ds_read_b128 v[162:165], v140
	ds_read_b128 v[166:169], v140 offset:1024
	ds_read_b128 v[170:173], v140 offset:2048
	ds_read_b128 v[174:177], v140 offset:3072
	s_cmp_eq_u32 s47, 12
	s_cselect_b32 s25, s9, s23
	s_cselect_b32 s24, s43, s22
	s_cselect_b32 s23, s1, s46
	s_cselect_b32 s22, s44, s45
	v_lshl_add_u64 v[140:141], s[20:21], 0, v[136:137]
	s_add_i32 m0, s3, 0xc000
	ds_read_b128 v[178:181], v145
	ds_read_b128 v[182:185], v145 offset:1024
	ds_read_b128 v[206:209], v145 offset:2048
	ds_read_b128 v[210:213], v145 offset:3072
	ds_read_b128 v[214:217], v145 offset:4096
	ds_read_b128 v[218:221], v145 offset:5120
	ds_read_b128 v[222:225], v145 offset:6144
	ds_read_b128 v[226:229], v145 offset:7168
	global_load_lds_dwordx4 v[140:141], off
	s_add_i32 m0, s3, 0xe000
	v_lshl_add_u64 v[140:141], s[20:21], 0, v[138:139]
	global_load_lds_dwordx4 v[140:141], off
	s_waitcnt lgkmcnt(8)
	s_barrier
	s_waitcnt lgkmcnt(7)
	v_mfma_f32_16x16x32_bf16 v[122:125], v[162:165], v[178:181], v[122:125]
	v_mfma_f32_16x16x32_bf16 v[114:117], v[170:173], v[178:181], v[114:117]
	s_waitcnt lgkmcnt(5)
	v_mfma_f32_16x16x32_bf16 v[106:109], v[162:165], v[206:209], v[106:109]
	v_mfma_f32_16x16x32_bf16 v[98:101], v[170:173], v[206:209], v[98:101]
	s_waitcnt lgkmcnt(3)
	v_mfma_f32_16x16x32_bf16 v[90:93], v[162:165], v[214:217], v[90:93]
	v_mfma_f32_16x16x32_bf16 v[82:85], v[170:173], v[214:217], v[82:85]
	s_waitcnt lgkmcnt(1)
	v_mfma_f32_16x16x32_bf16 v[74:77], v[162:165], v[222:225], v[74:77]
	v_mfma_f32_16x16x32_bf16 v[66:69], v[170:173], v[222:225], v[66:69]
	v_mfma_f32_16x16x32_bf16 v[122:125], v[166:169], v[182:185], v[122:125]
	v_mfma_f32_16x16x32_bf16 v[114:117], v[174:177], v[182:185], v[114:117]
	v_mfma_f32_16x16x32_bf16 v[106:109], v[166:169], v[210:213], v[106:109]
	v_mfma_f32_16x16x32_bf16 v[98:101], v[174:177], v[210:213], v[98:101]
	v_mfma_f32_16x16x32_bf16 v[90:93], v[166:169], v[218:221], v[90:93]
	v_mfma_f32_16x16x32_bf16 v[82:85], v[174:177], v[218:221], v[82:85]
	s_waitcnt lgkmcnt(0)
	v_mfma_f32_16x16x32_bf16 v[74:77], v[166:169], v[226:229], v[74:77]
	v_mfma_f32_16x16x32_bf16 v[66:69], v[174:177], v[226:229], v[66:69]
	s_barrier
	s_add_i32 s50, 0, 0x14000
	v_add_u32_e32 v140, s50, v143
	s_add_i32 s48, s48, s29
	ds_read_b128 v[230:233], v140
	ds_read_b128 v[234:237], v140 offset:1024
	ds_read_b128 v[238:241], v140 offset:2048
	ds_read_b128 v[242:245], v140 offset:3072
	v_lshl_add_u64 v[140:141], s[22:23], 0, v[0:1]
	s_mov_b32 m0, s48
	v_lshl_add_u64 v[186:187], s[22:23], 0, v[130:131]
	global_load_lds_dwordx4 v[140:141], off
	s_add_i32 m0, s48, 0x2000
	s_nop 0
	global_load_lds_dwordx4 v[186:187], off
	s_barrier
	s_waitcnt lgkmcnt(3)
	v_mfma_f32_16x16x32_bf16 v[126:129], v[230:233], v[178:181], v[126:129]
	s_waitcnt lgkmcnt(1)
	v_mfma_f32_16x16x32_bf16 v[118:121], v[238:241], v[178:181], v[118:121]
	v_mfma_f32_16x16x32_bf16 v[110:113], v[230:233], v[206:209], v[110:113]
	v_mfma_f32_16x16x32_bf16 v[102:105], v[238:241], v[206:209], v[102:105]
	v_mfma_f32_16x16x32_bf16 v[94:97], v[230:233], v[214:217], v[94:97]
	v_mfma_f32_16x16x32_bf16 v[86:89], v[238:241], v[214:217], v[86:89]
	v_mfma_f32_16x16x32_bf16 v[78:81], v[230:233], v[222:225], v[78:81]
	v_mfma_f32_16x16x32_bf16 v[70:73], v[238:241], v[222:225], v[70:73]
	v_mfma_f32_16x16x32_bf16 v[126:129], v[234:237], v[182:185], v[126:129]
	s_waitcnt lgkmcnt(0)
	v_mfma_f32_16x16x32_bf16 v[118:121], v[242:245], v[182:185], v[118:121]
	v_mfma_f32_16x16x32_bf16 v[110:113], v[234:237], v[210:213], v[110:113]
	v_mfma_f32_16x16x32_bf16 v[102:105], v[242:245], v[210:213], v[102:105]
	v_mfma_f32_16x16x32_bf16 v[94:97], v[234:237], v[218:221], v[94:97]
	v_mfma_f32_16x16x32_bf16 v[86:89], v[242:245], v[218:221], v[86:89]
	v_mfma_f32_16x16x32_bf16 v[78:81], v[234:237], v[226:229], v[78:81]
	v_mfma_f32_16x16x32_bf16 v[70:73], v[242:245], v[226:229], v[70:73]
	s_barrier
	s_mov_b32 m0, s3
	v_lshl_add_u64 v[246:247], s[24:25], 0, v[134:135]
	ds_read_b128 v[178:181], v145 offset:16384
	ds_read_b128 v[182:185], v145 offset:17408
	ds_read_b128 v[206:209], v145 offset:18432
	ds_read_b128 v[210:213], v145 offset:19456
	ds_read_b128 v[214:217], v145 offset:20480
	ds_read_b128 v[218:221], v145 offset:21504
	ds_read_b128 v[222:225], v145 offset:22528
	ds_read_b128 v[226:229], v145 offset:23552
	global_load_lds_dwordx4 v[246:247], off
	s_mov_b32 m0, s31
	v_lshl_add_u64 v[248:249], s[24:25], 0, v[132:133]
	global_load_lds_dwordx4 v[248:249], off
	s_barrier
	s_waitcnt lgkmcnt(7)
	v_mfma_f32_16x16x32_bf16 v[58:61], v[162:165], v[178:181], v[58:61]
	v_mfma_f32_16x16x32_bf16 v[50:53], v[170:173], v[178:181], v[50:53]
	s_waitcnt lgkmcnt(5)
	v_mfma_f32_16x16x32_bf16 v[42:45], v[162:165], v[206:209], v[42:45]
	v_mfma_f32_16x16x32_bf16 v[34:37], v[170:173], v[206:209], v[34:37]
	s_waitcnt lgkmcnt(3)
	v_mfma_f32_16x16x32_bf16 v[26:29], v[162:165], v[214:217], v[26:29]
	v_mfma_f32_16x16x32_bf16 v[18:21], v[170:173], v[214:217], v[18:21]
	s_waitcnt lgkmcnt(1)
	v_mfma_f32_16x16x32_bf16 v[10:13], v[162:165], v[222:225], v[10:13]
	v_mfma_f32_16x16x32_bf16 v[6:9], v[170:173], v[222:225], v[6:9]
	v_mfma_f32_16x16x32_bf16 v[58:61], v[166:169], v[182:185], v[58:61]
	v_mfma_f32_16x16x32_bf16 v[50:53], v[174:177], v[182:185], v[50:53]
	v_mfma_f32_16x16x32_bf16 v[42:45], v[166:169], v[210:213], v[42:45]
	v_mfma_f32_16x16x32_bf16 v[34:37], v[174:177], v[210:213], v[34:37]
	v_mfma_f32_16x16x32_bf16 v[26:29], v[166:169], v[218:221], v[26:29]
	v_mfma_f32_16x16x32_bf16 v[18:21], v[174:177], v[218:221], v[18:21]
	s_waitcnt lgkmcnt(0)
	v_mfma_f32_16x16x32_bf16 v[10:13], v[166:169], v[226:229], v[10:13]
	v_mfma_f32_16x16x32_bf16 v[6:9], v[174:177], v[226:229], v[6:9]
	s_barrier
	s_add_u32 s48, s22, 0x40000
	s_addc_u32 s49, s23, 0
	s_add_i32 s50, s50, s29
	s_mov_b32 m0, s50
	v_lshl_add_u64 v[162:163], s[48:49], 0, v[0:1]
	global_load_lds_dwordx4 v[162:163], off
	s_add_i32 m0, s50, 0x2000
	v_lshl_add_u64 v[162:163], s[48:49], 0, v[130:131]
	global_load_lds_dwordx4 v[162:163], off
	s_waitcnt vmcnt(6)
	s_barrier
	v_mfma_f32_16x16x32_bf16 v[62:65], v[230:233], v[178:181], v[62:65]
	v_mfma_f32_16x16x32_bf16 v[54:57], v[238:241], v[178:181], v[54:57]
	v_mfma_f32_16x16x32_bf16 v[46:49], v[230:233], v[206:209], v[46:49]
	v_mfma_f32_16x16x32_bf16 v[38:41], v[238:241], v[206:209], v[38:41]
	v_mfma_f32_16x16x32_bf16 v[30:33], v[230:233], v[214:217], v[30:33]
	v_mfma_f32_16x16x32_bf16 v[22:25], v[238:241], v[214:217], v[22:25]
	v_mfma_f32_16x16x32_bf16 v[14:17], v[230:233], v[222:225], v[14:17]
	v_mfma_f32_16x16x32_bf16 v[2:5], v[238:241], v[222:225], v[2:5]
	v_mfma_f32_16x16x32_bf16 v[62:65], v[234:237], v[182:185], v[62:65]
	v_mfma_f32_16x16x32_bf16 v[54:57], v[242:245], v[182:185], v[54:57]
	v_mfma_f32_16x16x32_bf16 v[46:49], v[234:237], v[210:213], v[46:49]
	v_mfma_f32_16x16x32_bf16 v[38:41], v[242:245], v[210:213], v[38:41]
	v_mfma_f32_16x16x32_bf16 v[30:33], v[234:237], v[218:221], v[30:33]
	v_mfma_f32_16x16x32_bf16 v[22:25], v[242:245], v[218:221], v[22:25]
	v_mfma_f32_16x16x32_bf16 v[14:17], v[234:237], v[226:229], v[14:17]
	v_mfma_f32_16x16x32_bf16 v[2:5], v[242:245], v[226:229], v[2:5]
	s_barrier
	s_add_i32 s48, 0, 0x18000
	v_add_u32_e32 v174, s48, v143
	ds_read_b128 v[162:165], v174
	ds_read_b128 v[166:169], v174 offset:1024
	ds_read_b128 v[170:173], v174 offset:2048
	ds_read_b128 v[174:177], v174 offset:3072
	s_add_u32 s24, s24, 0x40000
	s_addc_u32 s25, s25, 0
	s_mov_b32 m0, s34
	v_lshl_add_u64 v[230:231], s[24:25], 0, v[134:135]
	ds_read_b128 v[178:181], v145 offset:32768
	ds_read_b128 v[182:185], v145 offset:33792
	ds_read_b128 v[206:209], v145 offset:34816
	ds_read_b128 v[210:213], v145 offset:35840
	ds_read_b128 v[214:217], v145 offset:36864
	ds_read_b128 v[218:221], v145 offset:37888
	ds_read_b128 v[222:225], v145 offset:38912
	ds_read_b128 v[226:229], v145 offset:39936
	global_load_lds_dwordx4 v[230:231], off
	s_mov_b32 m0, s35
	v_lshl_add_u64 v[230:231], s[24:25], 0, v[132:133]
	global_load_lds_dwordx4 v[230:231], off
	s_waitcnt lgkmcnt(8)
	s_barrier
	s_waitcnt lgkmcnt(7)
	v_mfma_f32_16x16x32_bf16 v[122:125], v[162:165], v[178:181], v[122:125]
	v_mfma_f32_16x16x32_bf16 v[114:117], v[170:173], v[178:181], v[114:117]
	s_waitcnt lgkmcnt(5)
	v_mfma_f32_16x16x32_bf16 v[106:109], v[162:165], v[206:209], v[106:109]
	v_mfma_f32_16x16x32_bf16 v[98:101], v[170:173], v[206:209], v[98:101]
	s_waitcnt lgkmcnt(3)
	v_mfma_f32_16x16x32_bf16 v[90:93], v[162:165], v[214:217], v[90:93]
	v_mfma_f32_16x16x32_bf16 v[82:85], v[170:173], v[214:217], v[82:85]
	s_waitcnt lgkmcnt(1)
	v_mfma_f32_16x16x32_bf16 v[74:77], v[162:165], v[222:225], v[74:77]
	v_mfma_f32_16x16x32_bf16 v[66:69], v[170:173], v[222:225], v[66:69]
	v_mfma_f32_16x16x32_bf16 v[122:125], v[166:169], v[182:185], v[122:125]
	v_mfma_f32_16x16x32_bf16 v[114:117], v[174:177], v[182:185], v[114:117]
	v_mfma_f32_16x16x32_bf16 v[106:109], v[166:169], v[210:213], v[106:109]
	v_mfma_f32_16x16x32_bf16 v[98:101], v[174:177], v[210:213], v[98:101]
	v_mfma_f32_16x16x32_bf16 v[90:93], v[166:169], v[218:221], v[90:93]
	v_mfma_f32_16x16x32_bf16 v[82:85], v[174:177], v[218:221], v[82:85]
	s_waitcnt lgkmcnt(0)
	v_mfma_f32_16x16x32_bf16 v[74:77], v[166:169], v[226:229], v[74:77]
	v_mfma_f32_16x16x32_bf16 v[66:69], v[174:177], v[226:229], v[66:69]
	s_barrier
	s_add_i32 s24, 0, 0x1c000
	s_add_i32 s25, s48, s29
	v_add_u32_e32 v205, s24, v143
	v_lshl_add_u64 v[140:141], v[140:141], 0, s[94:95]
	s_mov_b32 m0, s25
	ds_read_b128 v[230:233], v205
	ds_read_b128 v[234:237], v205 offset:1024
	ds_read_b128 v[238:241], v205 offset:2048
	ds_read_b128 v[242:245], v205 offset:3072
	global_load_lds_dwordx4 v[140:141], off
	s_add_i32 m0, s25, 0x2000
	v_lshl_add_u64 v[140:141], v[186:187], 0, s[94:95]
	global_load_lds_dwordx4 v[140:141], off
	s_barrier
	s_waitcnt lgkmcnt(3)
	v_mfma_f32_16x16x32_bf16 v[126:129], v[230:233], v[178:181], v[126:129]
	s_waitcnt lgkmcnt(1)
	v_mfma_f32_16x16x32_bf16 v[118:121], v[238:241], v[178:181], v[118:121]
	v_mfma_f32_16x16x32_bf16 v[110:113], v[230:233], v[206:209], v[110:113]
	v_mfma_f32_16x16x32_bf16 v[102:105], v[238:241], v[206:209], v[102:105]
	v_mfma_f32_16x16x32_bf16 v[94:97], v[230:233], v[214:217], v[94:97]
	v_mfma_f32_16x16x32_bf16 v[86:89], v[238:241], v[214:217], v[86:89]
	v_mfma_f32_16x16x32_bf16 v[78:81], v[230:233], v[222:225], v[78:81]
	v_mfma_f32_16x16x32_bf16 v[70:73], v[238:241], v[222:225], v[70:73]
	v_mfma_f32_16x16x32_bf16 v[126:129], v[234:237], v[182:185], v[126:129]
	s_waitcnt lgkmcnt(0)
	v_mfma_f32_16x16x32_bf16 v[118:121], v[242:245], v[182:185], v[118:121]
	v_mfma_f32_16x16x32_bf16 v[110:113], v[234:237], v[210:213], v[110:113]
	v_mfma_f32_16x16x32_bf16 v[102:105], v[242:245], v[210:213], v[102:105]
	v_mfma_f32_16x16x32_bf16 v[94:97], v[234:237], v[218:221], v[94:97]
	v_mfma_f32_16x16x32_bf16 v[86:89], v[242:245], v[218:221], v[86:89]
	v_mfma_f32_16x16x32_bf16 v[78:81], v[234:237], v[226:229], v[78:81]
	v_mfma_f32_16x16x32_bf16 v[70:73], v[242:245], v[226:229], v[70:73]
	s_barrier
	s_mov_b32 m0, s37
	v_lshl_add_u64 v[140:141], v[246:247], 0, s[94:95]
	ds_read_b128 v[178:181], v145 offset:49152
	ds_read_b128 v[182:185], v145 offset:50176
	ds_read_b128 v[206:209], v145 offset:51200
	ds_read_b128 v[210:213], v145 offset:52224
	ds_read_b128 v[214:217], v145 offset:53248
	ds_read_b128 v[218:221], v145 offset:54272
	ds_read_b128 v[222:225], v145 offset:55296
	ds_read_b128 v[226:229], v145 offset:56320
	global_load_lds_dwordx4 v[140:141], off
	s_mov_b32 m0, s40
	v_lshl_add_u64 v[140:141], v[248:249], 0, s[94:95]
	global_load_lds_dwordx4 v[140:141], off
	s_barrier
	s_waitcnt lgkmcnt(7)
	v_mfma_f32_16x16x32_bf16 v[58:61], v[162:165], v[178:181], v[58:61]
	v_mfma_f32_16x16x32_bf16 v[50:53], v[170:173], v[178:181], v[50:53]
	s_waitcnt lgkmcnt(5)
	v_mfma_f32_16x16x32_bf16 v[42:45], v[162:165], v[206:209], v[42:45]
	v_mfma_f32_16x16x32_bf16 v[34:37], v[170:173], v[206:209], v[34:37]
	s_waitcnt lgkmcnt(3)
	v_mfma_f32_16x16x32_bf16 v[26:29], v[162:165], v[214:217], v[26:29]
	v_mfma_f32_16x16x32_bf16 v[18:21], v[170:173], v[214:217], v[18:21]
	s_waitcnt lgkmcnt(1)
	v_mfma_f32_16x16x32_bf16 v[10:13], v[162:165], v[222:225], v[10:13]
	v_mfma_f32_16x16x32_bf16 v[6:9], v[170:173], v[222:225], v[6:9]
	v_mfma_f32_16x16x32_bf16 v[58:61], v[166:169], v[182:185], v[58:61]
	v_mfma_f32_16x16x32_bf16 v[50:53], v[174:177], v[182:185], v[50:53]
	v_mfma_f32_16x16x32_bf16 v[42:45], v[166:169], v[210:213], v[42:45]
	v_mfma_f32_16x16x32_bf16 v[34:37], v[174:177], v[210:213], v[34:37]
	v_mfma_f32_16x16x32_bf16 v[26:29], v[166:169], v[218:221], v[26:29]
	v_mfma_f32_16x16x32_bf16 v[18:21], v[174:177], v[218:221], v[18:21]
	s_waitcnt lgkmcnt(0)
	v_mfma_f32_16x16x32_bf16 v[10:13], v[166:169], v[226:229], v[10:13]
	v_mfma_f32_16x16x32_bf16 v[6:9], v[174:177], v[226:229], v[6:9]
	s_barrier
	s_add_u32 s22, s22, 0x40080
	s_addc_u32 s23, s23, 0
	s_add_i32 s24, s24, s29
	s_mov_b32 m0, s24
	v_lshl_add_u64 v[140:141], s[22:23], 0, v[0:1]
	global_load_lds_dwordx4 v[140:141], off
	s_add_i32 m0, s24, 0x2000
	v_lshl_add_u64 v[140:141], s[22:23], 0, v[130:131]
	global_load_lds_dwordx4 v[140:141], off
	s_waitcnt vmcnt(6)
	s_barrier
	v_mfma_f32_16x16x32_bf16 v[62:65], v[230:233], v[178:181], v[62:65]
	v_mfma_f32_16x16x32_bf16 v[54:57], v[238:241], v[178:181], v[54:57]
	v_mfma_f32_16x16x32_bf16 v[46:49], v[230:233], v[206:209], v[46:49]
	v_mfma_f32_16x16x32_bf16 v[38:41], v[238:241], v[206:209], v[38:41]
	v_mfma_f32_16x16x32_bf16 v[30:33], v[230:233], v[214:217], v[30:33]
	v_mfma_f32_16x16x32_bf16 v[22:25], v[238:241], v[214:217], v[22:25]
	v_mfma_f32_16x16x32_bf16 v[14:17], v[230:233], v[222:225], v[14:17]
	v_mfma_f32_16x16x32_bf16 v[2:5], v[238:241], v[222:225], v[2:5]
	v_mfma_f32_16x16x32_bf16 v[62:65], v[234:237], v[182:185], v[62:65]
	v_mfma_f32_16x16x32_bf16 v[54:57], v[242:245], v[182:185], v[54:57]
	v_mfma_f32_16x16x32_bf16 v[46:49], v[234:237], v[210:213], v[46:49]
	v_mfma_f32_16x16x32_bf16 v[38:41], v[242:245], v[210:213], v[38:41]
	v_mfma_f32_16x16x32_bf16 v[30:33], v[234:237], v[218:221], v[30:33]
	v_mfma_f32_16x16x32_bf16 v[22:25], v[242:245], v[218:221], v[22:25]
	v_mfma_f32_16x16x32_bf16 v[14:17], v[234:237], v[226:229], v[14:17]
	v_mfma_f32_16x16x32_bf16 v[2:5], v[242:245], v[226:229], v[2:5]
	s_barrier
	s_add_i32 s47, s47, 2
	s_add_u32 s20, s20, 0x100
	s_addc_u32 s21, s21, 0
	s_add_u32 s45, s45, 0x100
	s_addc_u32 s46, s46, 0
	s_cmp_gt_u32 s47, 13
	s_cbranch_scc0 .LBB0_586
	v_pk_mul_f32 v[164:165], v[122:123], s[4:5] op_sel_hi:[1,0]
	v_pk_mul_f32 v[122:123], v[122:123], v[126:127]
	v_pk_mul_f32 v[126:127], v[114:115], s[4:5] op_sel_hi:[1,0]
	v_pk_mul_f32 v[114:115], v[114:115], v[118:119]
	v_exp_f32_e32 v126, v126
	v_exp_f32_e32 v127, v127
	v_pk_mul_f32 v[128:129], v[124:125], v[128:129]
	v_pk_mul_f32 v[124:125], v[124:125], s[4:5] op_sel_hi:[1,0]
	v_exp_f32_e32 v164, v164
	v_pk_add_f32 v[126:127], v[126:127], 1.0 op_sel_hi:[1,0]
	v_exp_f32_e32 v165, v165
	v_rcp_f32_e32 v126, v126
	v_rcp_f32_e32 v127, v127
	v_exp_f32_e32 v124, v124
	v_exp_f32_e32 v125, v125
	v_pk_add_f32 v[164:165], v[164:165], 1.0 op_sel_hi:[1,0]
	v_pk_mul_f32 v[118:119], v[126:127], v[114:115]
	v_pk_mul_f32 v[114:115], v[116:117], s[4:5] op_sel_hi:[1,0]
	v_pk_add_f32 v[124:125], v[124:125], 1.0 op_sel_hi:[1,0]
	v_exp_f32_e32 v114, v114
	v_exp_f32_e32 v115, v115
	v_rcp_f32_e32 v164, v164
	v_rcp_f32_e32 v165, v165
	v_rcp_f32_e32 v124, v124
	v_pk_add_f32 v[114:115], v[114:115], 1.0 op_sel_hi:[1,0]
	v_rcp_f32_e32 v125, v125
	v_rcp_f32_e32 v114, v114
	v_rcp_f32_e32 v115, v115
	v_lshl_or_b32 v140, s42, 7, v144
	v_ashrrev_i32_e32 v141, 31, v140
	v_lshl_add_u32 v162, s2, 8, v142
	v_lshl_add_u64 v[140:141], v[140:141], 1, s[14:15]
	v_pk_mul_f32 v[120:121], v[116:117], v[120:121]
	v_pk_mul_f32 v[122:123], v[164:165], v[122:123]
	v_pk_mul_f32 v[124:125], v[124:125], v[128:129]
	v_pk_mul_f32 v[120:121], v[114:115], v[120:121]
	v_mad_i64_i32 v[126:127], s[20:21], v162, s91, v[140:141]
	v_cvt_pk_bf16_f32 v114, v122, v123
	v_cvt_pk_bf16_f32 v115, v124, v125
	v_cvt_pk_bf16_f32 v116, v118, v119
	v_cvt_pk_bf16_f32 v117, v120, v121
	global_store_dwordx4 v[126:127], v[114:117], off
	v_pk_mul_f32 v[112:113], v[108:109], v[112:113]
	v_pk_mul_f32 v[108:109], v[108:109], s[4:5] op_sel_hi:[1,0]
	v_pk_mul_f32 v[114:115], v[106:107], s[4:5] op_sel_hi:[1,0]
	v_pk_mul_f32 v[106:107], v[106:107], v[110:111]
	v_pk_mul_f32 v[110:111], v[98:99], s[4:5] op_sel_hi:[1,0]
	v_pk_mul_f32 v[98:99], v[98:99], v[102:103]
	v_exp_f32_e32 v110, v110
	v_exp_f32_e32 v111, v111
	v_exp_f32_e32 v114, v114
	v_exp_f32_e32 v115, v115
	v_exp_f32_e32 v108, v108
	v_pk_add_f32 v[110:111], v[110:111], 1.0 op_sel_hi:[1,0]
	v_exp_f32_e32 v109, v109
	v_rcp_f32_e32 v110, v110
	v_rcp_f32_e32 v111, v111
	v_pk_add_f32 v[114:115], v[114:115], 1.0 op_sel_hi:[1,0]
	v_pk_add_f32 v[108:109], v[108:109], 1.0 op_sel_hi:[1,0]
	v_rcp_f32_e32 v114, v114
	v_pk_mul_f32 v[102:103], v[110:111], v[98:99]
	v_pk_mul_f32 v[98:99], v[100:101], s[4:5] op_sel_hi:[1,0]
	v_rcp_f32_e32 v115, v115
	v_exp_f32_e32 v98, v98
	v_exp_f32_e32 v99, v99
	v_rcp_f32_e32 v108, v108
	v_rcp_f32_e32 v109, v109
	v_or_b32_e32 v116, 16, v162
	v_pk_add_f32 v[98:99], v[98:99], 1.0 op_sel_hi:[1,0]
	v_pk_mul_f32 v[104:105], v[100:101], v[104:105]
	v_rcp_f32_e32 v98, v98
	v_rcp_f32_e32 v99, v99
	v_pk_mul_f32 v[106:107], v[114:115], v[106:107]
	v_pk_mul_f32 v[108:109], v[108:109], v[112:113]
	v_mad_i64_i32 v[110:111], s[20:21], v116, s91, v[140:141]
	v_pk_mul_f32 v[104:105], v[98:99], v[104:105]
	v_cvt_pk_bf16_f32 v98, v106, v107
	v_cvt_pk_bf16_f32 v99, v108, v109
	v_cvt_pk_bf16_f32 v100, v102, v103
	v_pk_mul_f32 v[96:97], v[92:93], v[96:97]
	v_cvt_pk_bf16_f32 v101, v104, v105
	global_store_dwordx4 v[110:111], v[98:101], off
	v_pk_mul_f32 v[92:93], v[92:93], s[4:5] op_sel_hi:[1,0]
	v_pk_mul_f32 v[88:89], v[84:85], v[88:89]
	v_pk_mul_f32 v[98:99], v[90:91], s[4:5] op_sel_hi:[1,0]
	v_pk_mul_f32 v[90:91], v[90:91], v[94:95]
	v_pk_mul_f32 v[94:95], v[82:83], s[4:5] op_sel_hi:[1,0]
	v_pk_mul_f32 v[82:83], v[82:83], v[86:87]
	v_exp_f32_e32 v94, v94
	v_exp_f32_e32 v95, v95
	v_exp_f32_e32 v98, v98
	v_exp_f32_e32 v99, v99
	v_exp_f32_e32 v92, v92
	v_pk_add_f32 v[94:95], v[94:95], 1.0 op_sel_hi:[1,0]
	v_exp_f32_e32 v93, v93
	v_rcp_f32_e32 v94, v94
	v_rcp_f32_e32 v95, v95
	v_pk_add_f32 v[98:99], v[98:99], 1.0 op_sel_hi:[1,0]
	v_pk_add_f32 v[92:93], v[92:93], 1.0 op_sel_hi:[1,0]
	v_rcp_f32_e32 v98, v98
	v_pk_mul_f32 v[86:87], v[94:95], v[82:83]
	v_pk_mul_f32 v[82:83], v[84:85], s[4:5] op_sel_hi:[1,0]
	v_rcp_f32_e32 v99, v99
	v_exp_f32_e32 v82, v82
	v_exp_f32_e32 v83, v83
	v_rcp_f32_e32 v92, v92
	v_rcp_f32_e32 v93, v93
	v_or_b32_e32 v100, 32, v162
	v_pk_add_f32 v[82:83], v[82:83], 1.0 op_sel_hi:[1,0]
	v_pk_mul_f32 v[90:91], v[98:99], v[90:91]
	v_rcp_f32_e32 v82, v82
	v_rcp_f32_e32 v83, v83
	v_pk_mul_f32 v[92:93], v[92:93], v[96:97]
	v_mad_i64_i32 v[94:95], s[20:21], v100, s91, v[140:141]
	v_pk_mul_f32 v[88:89], v[82:83], v[88:89]
	v_cvt_pk_bf16_f32 v82, v90, v91
	v_cvt_pk_bf16_f32 v83, v92, v93
	v_cvt_pk_bf16_f32 v84, v86, v87
	v_pk_mul_f32 v[80:81], v[76:77], v[80:81]
	v_cvt_pk_bf16_f32 v85, v88, v89
	global_store_dwordx4 v[94:95], v[82:85], off
	v_pk_mul_f32 v[76:77], v[76:77], s[4:5] op_sel_hi:[1,0]
	v_pk_mul_f32 v[72:73], v[68:69], v[72:73]
	v_pk_mul_f32 v[82:83], v[74:75], s[4:5] op_sel_hi:[1,0]
	v_pk_mul_f32 v[74:75], v[74:75], v[78:79]
	v_pk_mul_f32 v[78:79], v[66:67], s[4:5] op_sel_hi:[1,0]
	v_pk_mul_f32 v[66:67], v[66:67], v[70:71]
	v_exp_f32_e32 v78, v78
	v_exp_f32_e32 v79, v79
	v_exp_f32_e32 v82, v82
	v_exp_f32_e32 v83, v83
	v_exp_f32_e32 v76, v76
	v_pk_add_f32 v[78:79], v[78:79], 1.0 op_sel_hi:[1,0]
	v_exp_f32_e32 v77, v77
	v_rcp_f32_e32 v78, v78
	v_rcp_f32_e32 v79, v79
	v_pk_add_f32 v[82:83], v[82:83], 1.0 op_sel_hi:[1,0]
	v_pk_add_f32 v[76:77], v[76:77], 1.0 op_sel_hi:[1,0]
	v_rcp_f32_e32 v82, v82
	v_pk_mul_f32 v[70:71], v[78:79], v[66:67]
	v_pk_mul_f32 v[66:67], v[68:69], s[4:5] op_sel_hi:[1,0]
	v_rcp_f32_e32 v83, v83
	v_exp_f32_e32 v66, v66
	v_exp_f32_e32 v67, v67
	v_rcp_f32_e32 v76, v76
	v_rcp_f32_e32 v77, v77
	v_or_b32_e32 v84, 48, v162
	v_pk_add_f32 v[66:67], v[66:67], 1.0 op_sel_hi:[1,0]
	v_pk_mul_f32 v[74:75], v[82:83], v[74:75]
	v_rcp_f32_e32 v66, v66
	v_rcp_f32_e32 v67, v67
	v_pk_mul_f32 v[76:77], v[76:77], v[80:81]
	v_mad_i64_i32 v[78:79], s[20:21], v84, s91, v[140:141]
	v_pk_mul_f32 v[72:73], v[66:67], v[72:73]
	v_cvt_pk_bf16_f32 v66, v74, v75
	v_cvt_pk_bf16_f32 v67, v76, v77
	v_cvt_pk_bf16_f32 v68, v70, v71
	v_pk_mul_f32 v[64:65], v[60:61], v[64:65]
	v_cvt_pk_bf16_f32 v69, v72, v73
	global_store_dwordx4 v[78:79], v[66:69], off
	v_pk_mul_f32 v[60:61], v[60:61], s[4:5] op_sel_hi:[1,0]
	v_pk_mul_f32 v[56:57], v[52:53], v[56:57]
	v_pk_mul_f32 v[66:67], v[58:59], s[4:5] op_sel_hi:[1,0]
	v_pk_mul_f32 v[58:59], v[58:59], v[62:63]
	v_pk_mul_f32 v[62:63], v[50:51], s[4:5] op_sel_hi:[1,0]
	v_pk_mul_f32 v[50:51], v[50:51], v[54:55]
	v_exp_f32_e32 v62, v62
	v_exp_f32_e32 v63, v63
	v_exp_f32_e32 v66, v66
	v_exp_f32_e32 v67, v67
	v_exp_f32_e32 v60, v60
	v_pk_add_f32 v[62:63], v[62:63], 1.0 op_sel_hi:[1,0]
	v_exp_f32_e32 v61, v61
	v_rcp_f32_e32 v62, v62
	v_rcp_f32_e32 v63, v63
	v_pk_add_f32 v[66:67], v[66:67], 1.0 op_sel_hi:[1,0]
	v_pk_add_f32 v[60:61], v[60:61], 1.0 op_sel_hi:[1,0]
	v_rcp_f32_e32 v66, v66
	v_pk_mul_f32 v[54:55], v[62:63], v[50:51]
	v_pk_mul_f32 v[50:51], v[52:53], s[4:5] op_sel_hi:[1,0]
	v_rcp_f32_e32 v67, v67
	v_exp_f32_e32 v50, v50
	v_exp_f32_e32 v51, v51
	v_rcp_f32_e32 v60, v60
	v_rcp_f32_e32 v61, v61
	v_add_u32_e32 v68, 0x80, v162
	v_pk_add_f32 v[50:51], v[50:51], 1.0 op_sel_hi:[1,0]
	v_pk_mul_f32 v[58:59], v[66:67], v[58:59]
	v_rcp_f32_e32 v50, v50
	v_rcp_f32_e32 v51, v51
	v_pk_mul_f32 v[60:61], v[60:61], v[64:65]
	v_mad_i64_i32 v[62:63], s[20:21], v68, s91, v[140:141]
	v_pk_mul_f32 v[56:57], v[50:51], v[56:57]
	v_cvt_pk_bf16_f32 v50, v58, v59
	v_cvt_pk_bf16_f32 v51, v60, v61
	v_cvt_pk_bf16_f32 v52, v54, v55
	v_pk_mul_f32 v[48:49], v[44:45], v[48:49]
	v_cvt_pk_bf16_f32 v53, v56, v57
	global_store_dwordx4 v[62:63], v[50:53], off
	v_pk_mul_f32 v[44:45], v[44:45], s[4:5] op_sel_hi:[1,0]
	v_pk_mul_f32 v[40:41], v[36:37], v[40:41]
	v_pk_mul_f32 v[50:51], v[42:43], s[4:5] op_sel_hi:[1,0]
	v_pk_mul_f32 v[42:43], v[42:43], v[46:47]
	v_pk_mul_f32 v[46:47], v[34:35], s[4:5] op_sel_hi:[1,0]
	v_pk_mul_f32 v[34:35], v[34:35], v[38:39]
	v_exp_f32_e32 v46, v46
	v_exp_f32_e32 v47, v47
	v_exp_f32_e32 v50, v50
	v_exp_f32_e32 v51, v51
	v_exp_f32_e32 v44, v44
	v_pk_add_f32 v[46:47], v[46:47], 1.0 op_sel_hi:[1,0]
	v_exp_f32_e32 v45, v45
	v_rcp_f32_e32 v46, v46
	v_rcp_f32_e32 v47, v47
	v_pk_add_f32 v[50:51], v[50:51], 1.0 op_sel_hi:[1,0]
	v_pk_add_f32 v[44:45], v[44:45], 1.0 op_sel_hi:[1,0]
	v_rcp_f32_e32 v50, v50
	v_pk_mul_f32 v[38:39], v[46:47], v[34:35]
	v_pk_mul_f32 v[34:35], v[36:37], s[4:5] op_sel_hi:[1,0]
	v_rcp_f32_e32 v51, v51
	v_exp_f32_e32 v34, v34
	v_exp_f32_e32 v35, v35
	v_rcp_f32_e32 v44, v44
	v_rcp_f32_e32 v45, v45
	v_add_u32_e32 v52, 0x90, v162
	v_pk_add_f32 v[34:35], v[34:35], 1.0 op_sel_hi:[1,0]
	v_pk_mul_f32 v[42:43], v[50:51], v[42:43]
	v_rcp_f32_e32 v34, v34
	v_rcp_f32_e32 v35, v35
	v_pk_mul_f32 v[44:45], v[44:45], v[48:49]
	v_mad_i64_i32 v[46:47], s[20:21], v52, s91, v[140:141]
	v_pk_mul_f32 v[40:41], v[34:35], v[40:41]
	v_cvt_pk_bf16_f32 v34, v42, v43
	v_cvt_pk_bf16_f32 v35, v44, v45
	v_cvt_pk_bf16_f32 v36, v38, v39
	v_pk_mul_f32 v[32:33], v[28:29], v[32:33]
	v_cvt_pk_bf16_f32 v37, v40, v41
	global_store_dwordx4 v[46:47], v[34:37], off
	v_pk_mul_f32 v[28:29], v[28:29], s[4:5] op_sel_hi:[1,0]
	v_pk_mul_f32 v[24:25], v[20:21], v[24:25]
	v_pk_mul_f32 v[34:35], v[26:27], s[4:5] op_sel_hi:[1,0]
	v_pk_mul_f32 v[26:27], v[26:27], v[30:31]
	v_pk_mul_f32 v[30:31], v[18:19], s[4:5] op_sel_hi:[1,0]
	v_pk_mul_f32 v[18:19], v[18:19], v[22:23]
	v_exp_f32_e32 v30, v30
	v_exp_f32_e32 v31, v31
	v_exp_f32_e32 v34, v34
	v_exp_f32_e32 v35, v35
	v_exp_f32_e32 v28, v28
	v_pk_add_f32 v[30:31], v[30:31], 1.0 op_sel_hi:[1,0]
	v_exp_f32_e32 v29, v29
	v_rcp_f32_e32 v30, v30
	v_rcp_f32_e32 v31, v31
	v_pk_add_f32 v[34:35], v[34:35], 1.0 op_sel_hi:[1,0]
	v_pk_add_f32 v[28:29], v[28:29], 1.0 op_sel_hi:[1,0]
	v_rcp_f32_e32 v34, v34
	v_pk_mul_f32 v[22:23], v[30:31], v[18:19]
	v_pk_mul_f32 v[18:19], v[20:21], s[4:5] op_sel_hi:[1,0]
	v_rcp_f32_e32 v35, v35
	v_exp_f32_e32 v18, v18
	v_exp_f32_e32 v19, v19
	v_rcp_f32_e32 v28, v28
	v_rcp_f32_e32 v29, v29
	v_add_u32_e32 v36, 0xa0, v162
	v_pk_add_f32 v[18:19], v[18:19], 1.0 op_sel_hi:[1,0]
	v_pk_mul_f32 v[26:27], v[34:35], v[26:27]
	v_rcp_f32_e32 v18, v18
	v_rcp_f32_e32 v19, v19
	v_pk_mul_f32 v[28:29], v[28:29], v[32:33]
	v_mad_i64_i32 v[30:31], s[20:21], v36, s91, v[140:141]
	v_pk_mul_f32 v[24:25], v[18:19], v[24:25]
	v_cvt_pk_bf16_f32 v18, v26, v27
	v_cvt_pk_bf16_f32 v19, v28, v29
	v_cvt_pk_bf16_f32 v20, v22, v23
	v_pk_mul_f32 v[2:3], v[6:7], v[2:3]
	v_cvt_pk_bf16_f32 v21, v24, v25
	global_store_dwordx4 v[30:31], v[18:21], off
	v_pk_mul_f32 v[16:17], v[12:13], v[16:17]
	v_pk_mul_f32 v[12:13], v[12:13], s[4:5] op_sel_hi:[1,0]
	v_pk_mul_f32 v[18:19], v[10:11], s[4:5] op_sel_hi:[1,0]
	v_pk_mul_f32 v[10:11], v[10:11], v[14:15]
	v_pk_mul_f32 v[14:15], v[6:7], s[4:5] op_sel_hi:[1,0]
	v_exp_f32_e32 v18, v18
	v_exp_f32_e32 v14, v14
	v_exp_f32_e32 v15, v15
	v_exp_f32_e32 v19, v19
	v_exp_f32_e32 v12, v12
	v_exp_f32_e32 v13, v13
	v_pk_add_f32 v[14:15], v[14:15], 1.0 op_sel_hi:[1,0]
	v_pk_add_f32 v[18:19], v[18:19], 1.0 op_sel_hi:[1,0]
	v_rcp_f32_e32 v14, v14
	v_rcp_f32_e32 v15, v15
	v_pk_add_f32 v[12:13], v[12:13], 1.0 op_sel_hi:[1,0]
	v_rcp_f32_e32 v18, v18
	v_rcp_f32_e32 v19, v19
	v_pk_mul_f32 v[6:7], v[14:15], v[2:3]
	v_pk_mul_f32 v[2:3], v[8:9], s[4:5] op_sel_hi:[1,0]
	v_rcp_f32_e32 v12, v12
	v_exp_f32_e32 v2, v2
	v_exp_f32_e32 v3, v3
	v_rcp_f32_e32 v13, v13
	v_add_u32_e32 v20, 0xb0, v162
	v_mad_i64_i32 v[14:15], s[20:21], v20, s91, v[140:141]
	v_pk_add_f32 v[2:3], v[2:3], 1.0 op_sel_hi:[1,0]
	v_pk_mul_f32 v[4:5], v[8:9], v[4:5]
	v_rcp_f32_e32 v2, v2
	v_rcp_f32_e32 v3, v3
	s_and_b64 vcc, exec, s[38:39]
	s_mov_b32 s42, s0
	s_mov_b32 s2, s8
	s_mov_b64 s[22:23], s[18:19]
	s_mov_b64 s[20:21], s[16:17]
	v_pk_mul_f32 v[10:11], v[18:19], v[10:11]
	v_pk_mul_f32 v[12:13], v[12:13], v[16:17]
	v_pk_mul_f32 v[8:9], v[2:3], v[4:5]
	v_cvt_pk_bf16_f32 v2, v10, v11
	v_cvt_pk_bf16_f32 v3, v12, v13
	v_cvt_pk_bf16_f32 v4, v6, v7
	s_nop 0
	v_cvt_pk_bf16_f32 v5, v8, v9
	global_store_dwordx4 v[14:15], v[2:5], off
	s_cbranch_vccz .LBB0_579
	s_waitcnt vmcnt(0)
	s_cmpk_gt_u32 s26, 0xff
	s_cbranch_scc1 .LBB0_590
	s_barrier
